# GEMM: first K-loop iteration peeled per tile so accumulators start from inline 0 (no 128-mov zeroing per tile)
# speedup vs baseline: 1.0164x; 1.0057x over previous
; template <class Epi, class Sched, bool ALIGN_EPI = false, bool SP2 = false>
; __device__ __forceinline__ void gemm_phase(PG8_LAS unsigned char* lds, const Gemm g, const Sched& S, const Epi& E) {
;     ...
;         const bool has_next = S.next(ui + 1, nxt);
;         const char* nA = has_next ? (const char*)g.A + (size_t)nxt.pm * tstep : cA; const char* nB = has_next ? (const char*)g.Bt + (size_t)nxt.pn * tstep : cB;
;         for (int t = 0; t < nt; t += 2) {
;             const bool last = (t == nt - 2);
;             const char* a1 = cA + (size_t)(t + 1) * kstep;
;             const char* a2 = last ? nA : cA + (size_t)(t + 2) * kstep; const char* b2 = last ? nB : cB + (size_t)(t + 2) * kstep;
;             const char* a3 = a2 + kstep; const char* b3 = b2 + kstep;
;     ...
;         cur = nxt; cA = nA; cB = nB; ++ui;
.LBB0_241:
	s_ashr_i32 s51, s50, 31
	s_lshl_b64 s[30:31], s[50:51], 19
	s_add_u32 s56, s96, s30
	s_addc_u32 s57, s97, s31
	s_and_b64 s[30:31], s[54:55], exec
	s_cselect_b32 s1, s57, s19
	s_cselect_b32 s30, s56, s18
	s_ashr_i32 s49, s48, 31
	s_lshl_b64 s[34:35], s[48:49], 19
	s_add_u32 s58, s25, s34
	s_addc_u32 s59, s26, s35
	s_and_b64 s[34:35], s[54:55], exec
	s_cselect_b32 s31, s59, s37
	s_cselect_b32 s34, s58, s36
	s_add_u32 s18, s18, 0x40080
	s_addc_u32 s19, s19, 0
	s_add_u32 s35, s36, 0x100

; template <class Epi, class Sched, bool ALIGN_EPI = false, bool SP2 = false>
; __device__ __forceinline__ void gemm_phase(PG8_LAS unsigned char* lds, const Gemm g, const Sched& S, const Epi& E) {
;     ...
; #pragma unroll
;         for (int a = 0; a < 2; ++a)
; #pragma unroll
;             for (int b = 0; b < 2; ++b)
; #pragma unroll
;                 for (int m = 0; m < 4; ++m)
; #pragma unroll
;                     for (int n = 0; n < 2; ++n) acc[a][b][m][n] = (f32x4){0.f, 0.f, 0.f, 0.f};
;         cur = nxt; cA = nA; cB = nB; ++ui;
	s_addc_u32 s49, s37, 0
	s_mov_b32 s51, -2


; template <class Epi, class Sched, bool ALIGN_EPI = false, bool SP2 = false>
; __device__ __forceinline__ void gemm_phase(PG8_LAS unsigned char* lds, const Gemm g, const Sched& S, const Epi& E) {
;     ...
; #pragma unroll
;         for (int a = 0; a < 2; ++a)
; #pragma unroll
;             for (int b = 0; b < 2; ++b)
; #pragma unroll
;                 for (int m = 0; m < 4; ++m)
; #pragma unroll
;                     for (int n = 0; n < 2; ++n) acc[a][b][m][n] = (f32x4){0.f, 0.f, 0.f, 0.f};
	s_waitcnt vmcnt(0)


; #define PG8_STAGE(bufoff, gbase, voff) do { _Pragma("unroll") for (int _i = 0; _i < 2; ++_i) \
;         __builtin_amdgcn_global_load_lds((const unsigned*)((const char*)(gbase) + (voff)[_i]), (PG8_LAS unsigned*)(lds + (bufoff) + ldsw + _i * 8192), 16, 0, 0); } while (0)
; #define PG8_LDA(dst, b, h) do { _Pragma("unroll") for (int m = 0; m < 4; ++m) _Pragma("unroll") for (int k = 0; k < 2; ++k) dst[m][k] = *(const PG8_LAS bf16x8*)(lds + PG8_SA(b, h) + aoff + m * 2048 + k * 1024); } while (0)
; #define PG8_LDB(dst, b, h) do { _Pragma("unroll") for (int n = 0; n < 2; ++n) _Pragma("unroll") for (int k = 0; k < 2; ++k) dst[n][k] = *(const PG8_LAS bf16x8*)(lds + PG8_SB(b, h) + boff + n * 2048 + k * 1024); } while (0)
; #define PG8_MMA(ai, bj, At, Bt) do { __builtin_amdgcn_s_setprio(1); _Pragma("unroll") for (int m = 0; m < 4; ++m) _Pragma("unroll") for (int n = 0; n < 2; ++n) _Pragma("unroll") for (int k = 0; k < 2; ++k) \
;         acc[ai][bj][m][n] = __builtin_amdgcn_mfma_f32_16x16x32_bf16(Bt[n][k], At[m][k], acc[ai][bj][m][n], 0, 0, 0); __builtin_amdgcn_s_setprio(0); } while (0)
; #define PG8_WAIT_V(n) asm volatile("s_waitcnt vmcnt(" #n ")" ::: "memory")
; #define PG8_WAIT_L(n) asm volatile("s_waitcnt lgkmcnt(" #n ")" ::: "memory")
; #define PG8_BAR __builtin_amdgcn_s_barrier()
; #define PG8_SCHED __builtin_amdgcn_sched_barrier(0)
; template <class Epi, class Sched, bool ALIGN_EPI = false, bool SP2 = false>
; __device__ __forceinline__ void gemm_phase(PG8_LAS unsigned char* lds, const Gemm g, const Sched& S, const Epi& E) {
;     ...
;             const bool last = (t == nt - 2);
;             const char* a1 = cA + (size_t)(t + 1) * kstep;
;             const char* a2 = last ? nA : cA + (size_t)(t + 2) * kstep; const char* b2 = last ? nB : cB + (size_t)(t + 2) * kstep;
;             const char* a3 = a2 + kstep; const char* b3 = b2 + kstep;
;             if (last && has_next) S.a_ready(nxt);
;             if constexpr (SP2) {
;             PG8_LDB(B0, 0, 0); PG8_LDB(B1, 0, 1); PG8_SCHED; PG8_LDA(At, 0, 0); PG8_STAGE(PG8_SA(1, 1), a1 + hstep, voffA);
;             PG8_WAIT_V(8); PG8_WAIT_L(0); PG8_BAR; PG8_MMA(0, 0, At, B0); PG8_MMA(0, 1, At, B1); PG8_BAR; PG8_SCHED;
;             PG8_LDA(At, 0, 1); PG8_STAGE(PG8_SB(0, 0), b2, voffB); PG8_STAGE(PG8_SB(0, 1), b2 + hstep, voffB); PG8_STAGE(PG8_SA(0, 0), a2, voffA);
	s_add_u32 s36, s18, 0xfffc0080
	s_addc_u32 s37, s19, -1
	s_add_i32 s52, 0, 0x10000
	s_cmp_eq_u32 s51, 12
	s_cselect_b32 s63, s1, s37
	s_cselect_b32 s62, s30, s36
	s_cselect_b32 s37, s31, s49
	s_cselect_b32 s36, s34, s35
	s_add_i32 s67, 0, 0x14000
	v_add_u32_e32 v110, s52, v180
	v_add_u32_e32 v170, s67, v180
	ds_read_b128 v[98:101], v110
	ds_read_b128 v[102:105], v110 offset:1024
	ds_read_b128 v[106:109], v110 offset:2048
	ds_read_b128 v[110:113], v110 offset:3072
	ds_read_b128 v[158:161], v170
	ds_read_b128 v[162:165], v170 offset:1024
	ds_read_b128 v[166:169], v170 offset:2048
	ds_read_b128 v[170:173], v170 offset:3072
	v_lshl_add_u64 v[174:175], s[18:19], 0, v[154:155]
	s_add_i32 m0, s27, 0xc000
	ds_read_b128 v[184:187], v182
	ds_read_b128 v[194:197], v182 offset:1024
	ds_read_b128 v[198:201], v182 offset:2048
	ds_read_b128 v[202:205], v182 offset:3072
	ds_read_b128 v[206:209], v182 offset:4096
	ds_read_b128 v[210:213], v182 offset:5120
	ds_read_b128 v[214:217], v182 offset:6144
	ds_read_b128 v[218:221], v182 offset:7168
	global_load_lds_dwordx4 v[174:175], off
	v_lshl_add_u64 v[174:175], s[18:19], 0, v[156:157]
	s_add_i32 m0, s27, 0xe000
	s_nop 0
	global_load_lds_dwordx4 v[174:175], off
	s_waitcnt vmcnt(8)
	s_waitcnt lgkmcnt(0)
	s_barrier
	s_setprio 1
	s_waitcnt lgkmcnt(0)
	v_mfma_f32_16x16x32_bf16 v[142:145], v[98:101], v[184:187], 0
	v_mfma_f32_16x16x32_bf16 v[138:141], v[106:109], v[184:187], 0
	v_mfma_f32_16x16x32_bf16 v[126:129], v[98:101], v[198:201], 0
	v_mfma_f32_16x16x32_bf16 v[122:125], v[106:109], v[198:201], 0
	v_mfma_f32_16x16x32_bf16 v[94:97], v[98:101], v[206:209], 0
	v_mfma_f32_16x16x32_bf16 v[90:93], v[106:109], v[206:209], 0
	v_mfma_f32_16x16x32_bf16 v[78:81], v[98:101], v[214:217], 0
	v_mfma_f32_16x16x32_bf16 v[74:77], v[106:109], v[214:217], 0
	v_mfma_f32_16x16x32_bf16 v[142:145], v[102:105], v[194:197], v[142:145]
	v_mfma_f32_16x16x32_bf16 v[138:141], v[110:113], v[194:197], v[138:141]
	v_mfma_f32_16x16x32_bf16 v[126:129], v[102:105], v[202:205], v[126:129]
	v_mfma_f32_16x16x32_bf16 v[122:125], v[110:113], v[202:205], v[122:125]
	v_mfma_f32_16x16x32_bf16 v[94:97], v[102:105], v[210:213], v[94:97]
	v_mfma_f32_16x16x32_bf16 v[90:93], v[110:113], v[210:213], v[90:93]
	v_mfma_f32_16x16x32_bf16 v[78:81], v[102:105], v[218:221], v[78:81]
	v_mfma_f32_16x16x32_bf16 v[74:77], v[110:113], v[218:221], v[74:77]
	s_setprio 0
	s_setprio 1
	v_mfma_f32_16x16x32_bf16 v[134:137], v[158:161], v[184:187], 0
	v_mfma_f32_16x16x32_bf16 v[130:133], v[166:169], v[184:187], 0
	v_mfma_f32_16x16x32_bf16 v[118:121], v[158:161], v[198:201], 0
	v_mfma_f32_16x16x32_bf16 v[114:117], v[166:169], v[198:201], 0
	v_mfma_f32_16x16x32_bf16 v[86:89], v[158:161], v[206:209], 0
	v_mfma_f32_16x16x32_bf16 v[82:85], v[166:169], v[206:209], 0
	v_mfma_f32_16x16x32_bf16 v[70:73], v[158:161], v[214:217], 0
	v_mfma_f32_16x16x32_bf16 v[66:69], v[166:169], v[214:217], 0
	v_mfma_f32_16x16x32_bf16 v[134:137], v[162:165], v[194:197], v[134:137]
	v_mfma_f32_16x16x32_bf16 v[130:133], v[170:173], v[194:197], v[130:133]
	v_mfma_f32_16x16x32_bf16 v[118:121], v[162:165], v[202:205], v[118:121]
	v_mfma_f32_16x16x32_bf16 v[114:117], v[170:173], v[202:205], v[114:117]
	v_mfma_f32_16x16x32_bf16 v[86:89], v[162:165], v[210:213], v[86:89]
	v_mfma_f32_16x16x32_bf16 v[82:85], v[170:173], v[210:213], v[82:85]
	v_mfma_f32_16x16x32_bf16 v[70:73], v[162:165], v[218:221], v[70:73]
	v_mfma_f32_16x16x32_bf16 v[66:69], v[170:173], v[218:221], v[66:69]
	s_setprio 0
	s_barrier
	s_add_i32 s52, s52, s24
	v_lshl_add_u64 v[174:175], s[36:37], 0, v[0:1]
	s_mov_b32 m0, s52
	ds_read_b128 v[184:187], v182 offset:16384
	ds_read_b128 v[194:197], v182 offset:17408
	ds_read_b128 v[198:201], v182 offset:18432
	ds_read_b128 v[202:205], v182 offset:19456
	ds_read_b128 v[206:209], v182 offset:20480
	ds_read_b128 v[210:213], v182 offset:21504
	ds_read_b128 v[214:217], v182 offset:22528
	ds_read_b128 v[218:221], v182 offset:23552
	global_load_lds_dwordx4 v[174:175], off
	s_add_i32 m0, s52, 0x2000
	s_add_u32 s52, s36, 0x40000
	v_lshl_add_u64 v[178:179], s[36:37], 0, v[150:151]
	s_addc_u32 s53, s37, 0
	s_add_i32 s67, s67, s24
	global_load_lds_dwordx4 v[178:179], off
	v_lshl_add_u64 v[188:189], s[52:53], 0, v[0:1]
	s_mov_b32 m0, s67
	v_lshl_add_u64 v[222:223], s[62:63], 0, v[148:149]
	global_load_lds_dwordx4 v[188:189], off
	v_lshl_add_u64 v[188:189], s[52:53], 0, v[150:151]
	s_add_i32 m0, s67, 0x2000
	s_nop 0
	global_load_lds_dwordx4 v[188:189], off
	v_lshl_add_u64 v[188:189], s[62:63], 0, v[146:147]
	s_mov_b32 m0, s27
	s_nop 0
	global_load_lds_dwordx4 v[188:189], off
	s_mov_b32 m0, s28
	s_nop 0
	global_load_lds_dwordx4 v[222:223], off
	s_waitcnt vmcnt(8)
	s_waitcnt lgkmcnt(0)
	s_barrier
; #define PG8_STAGE(bufoff, gbase, voff) do { _Pragma("unroll") for (int _i = 0; _i < 2; ++_i) \
;         __builtin_amdgcn_global_load_lds((const unsigned*)((const char*)(gbase) + (voff)[_i]), (PG8_LAS unsigned*)(lds + (bufoff) + ldsw + _i * 8192), 16, 0, 0); } while (0)
; #define PG8_LDA(dst, b, h) do { _Pragma("unroll") for (int m = 0; m < 4; ++m) _Pragma("unroll") for (int k = 0; k < 2; ++k) dst[m][k] = *(const PG8_LAS bf16x8*)(lds + PG8_SA(b, h) + aoff + m * 2048 + k * 1024); } while (0)
; #define PG8_LDB(dst, b, h) do { _Pragma("unroll") for (int n = 0; n < 2; ++n) _Pragma("unroll") for (int k = 0; k < 2; ++k) dst[n][k] = *(const PG8_LAS bf16x8*)(lds + PG8_SB(b, h) + boff + n * 2048 + k * 1024); } while (0)
; #define PG8_MMA(ai, bj, At, Bt) do { __builtin_amdgcn_s_setprio(1); _Pragma("unroll") for (int m = 0; m < 4; ++m) _Pragma("unroll") for (int n = 0; n < 2; ++n) _Pragma("unroll") for (int k = 0; k < 2; ++k) \
;         acc[ai][bj][m][n] = __builtin_amdgcn_mfma_f32_16x16x32_bf16(Bt[n][k], At[m][k], acc[ai][bj][m][n], 0, 0, 0); __builtin_amdgcn_s_setprio(0); } while (0)
; #define PG8_WAIT_V(n) asm volatile("s_waitcnt vmcnt(" #n ")" ::: "memory")
; #define PG8_WAIT_L(n) asm volatile("s_waitcnt lgkmcnt(" #n ")" ::: "memory")
; #define PG8_BAR __builtin_amdgcn_s_barrier()
; #define PG8_SCHED __builtin_amdgcn_sched_barrier(0)
; template <class Epi, class Sched, bool ALIGN_EPI = false, bool SP2 = false>
; __device__ __forceinline__ void gemm_phase(PG8_LAS unsigned char* lds, const Gemm g, const Sched& S, const Epi& E) {
;     ...
;             PG8_WAIT_V(8); PG8_WAIT_L(0); PG8_BAR; PG8_MMA(1, 0, At, B0); PG8_MMA(1, 1, At, B1); PG8_BAR; PG8_SCHED;
;             PG8_LDB(B0, 1, 0); PG8_LDB(B1, 1, 1); PG8_SCHED; PG8_LDA(At, 1, 0); PG8_STAGE(PG8_SA(0, 1), a2 + hstep, voffA);
;             PG8_WAIT_V(8); PG8_WAIT_L(0); PG8_BAR; PG8_MMA(0, 0, At, B0); PG8_MMA(0, 1, At, B1); PG8_BAR; PG8_SCHED;
	s_setprio 1
	s_waitcnt lgkmcnt(0)
	v_mfma_f32_16x16x32_bf16 v[62:65], v[98:101], v[184:187], 0
	v_mfma_f32_16x16x32_bf16 v[58:61], v[106:109], v[184:187], 0
	v_mfma_f32_16x16x32_bf16 v[46:49], v[98:101], v[198:201], 0
	v_mfma_f32_16x16x32_bf16 v[42:45], v[106:109], v[198:201], 0
	v_mfma_f32_16x16x32_bf16 v[30:33], v[98:101], v[206:209], 0
	v_mfma_f32_16x16x32_bf16 v[26:29], v[106:109], v[206:209], 0
	v_mfma_f32_16x16x32_bf16 v[14:17], v[98:101], v[214:217], 0
	v_mfma_f32_16x16x32_bf16 v[10:13], v[106:109], v[214:217], 0
	v_mfma_f32_16x16x32_bf16 v[62:65], v[102:105], v[194:197], v[62:65]
	v_mfma_f32_16x16x32_bf16 v[58:61], v[110:113], v[194:197], v[58:61]
	v_mfma_f32_16x16x32_bf16 v[46:49], v[102:105], v[202:205], v[46:49]
	v_mfma_f32_16x16x32_bf16 v[42:45], v[110:113], v[202:205], v[42:45]
	v_mfma_f32_16x16x32_bf16 v[30:33], v[102:105], v[210:213], v[30:33]
	v_mfma_f32_16x16x32_bf16 v[26:29], v[110:113], v[210:213], v[26:29]
	v_mfma_f32_16x16x32_bf16 v[14:17], v[102:105], v[218:221], v[14:17]
	v_mfma_f32_16x16x32_bf16 v[10:13], v[110:113], v[218:221], v[10:13]
	s_setprio 0
	s_setprio 1
	v_mfma_f32_16x16x32_bf16 v[54:57], v[158:161], v[184:187], 0
	v_mfma_f32_16x16x32_bf16 v[50:53], v[166:169], v[184:187], 0
	v_mfma_f32_16x16x32_bf16 v[38:41], v[158:161], v[198:201], 0
	v_mfma_f32_16x16x32_bf16 v[34:37], v[166:169], v[198:201], 0
	v_mfma_f32_16x16x32_bf16 v[22:25], v[158:161], v[206:209], 0
	v_mfma_f32_16x16x32_bf16 v[18:21], v[166:169], v[206:209], 0
	v_mfma_f32_16x16x32_bf16 v[6:9], v[158:161], v[214:217], 0
	v_mfma_f32_16x16x32_bf16 v[2:5], v[166:169], v[214:217], 0
	v_mfma_f32_16x16x32_bf16 v[54:57], v[162:165], v[194:197], v[54:57]
	v_mfma_f32_16x16x32_bf16 v[50:53], v[170:173], v[194:197], v[50:53]
	v_mfma_f32_16x16x32_bf16 v[38:41], v[162:165], v[202:205], v[38:41]
	v_mfma_f32_16x16x32_bf16 v[34:37], v[170:173], v[202:205], v[34:37]
	v_mfma_f32_16x16x32_bf16 v[22:25], v[162:165], v[210:213], v[22:25]
	v_mfma_f32_16x16x32_bf16 v[18:21], v[170:173], v[210:213], v[18:21]
	v_mfma_f32_16x16x32_bf16 v[6:9], v[162:165], v[218:221], v[6:9]
	v_mfma_f32_16x16x32_bf16 v[2:5], v[170:173], v[218:221], v[2:5]
	s_setprio 0
	s_barrier
	s_add_i32 s67, 0, 0x18000
	s_add_i32 s68, 0, 0x1c000
	v_add_u32_e32 v110, s67, v180
	v_add_u32_e32 v170, s68, v180
	ds_read_b128 v[98:101], v110
	ds_read_b128 v[102:105], v110 offset:1024
	ds_read_b128 v[106:109], v110 offset:2048
	ds_read_b128 v[110:113], v110 offset:3072
	ds_read_b128 v[158:161], v170
	ds_read_b128 v[162:165], v170 offset:1024
	ds_read_b128 v[166:169], v170 offset:2048
	ds_read_b128 v[170:173], v170 offset:3072
	s_add_u32 s52, s62, 0x40000
	s_addc_u32 s53, s63, 0
	s_mov_b32 m0, s29
	v_lshl_add_u64 v[224:225], s[52:53], 0, v[146:147]
	ds_read_b128 v[184:187], v182 offset:32768
	ds_read_b128 v[194:197], v182 offset:33792
	ds_read_b128 v[198:201], v182 offset:34816
	ds_read_b128 v[202:205], v182 offset:35840
	ds_read_b128 v[206:209], v182 offset:36864
	ds_read_b128 v[210:213], v182 offset:37888
	ds_read_b128 v[214:217], v182 offset:38912
	ds_read_b128 v[218:221], v182 offset:39936
	global_load_lds_dwordx4 v[224:225], off
	v_lshl_add_u64 v[224:225], s[52:53], 0, v[148:149]
	s_mov_b32 m0, s61
	s_nop 0
	global_load_lds_dwordx4 v[224:225], off
	s_waitcnt vmcnt(8)
	s_waitcnt lgkmcnt(0)
	s_barrier
	s_setprio 1
	s_waitcnt lgkmcnt(0)
	v_mfma_f32_16x16x32_bf16 v[142:145], v[98:101], v[184:187], v[142:145]
	v_mfma_f32_16x16x32_bf16 v[138:141], v[106:109], v[184:187], v[138:141]
	v_mfma_f32_16x16x32_bf16 v[126:129], v[98:101], v[198:201], v[126:129]
	v_mfma_f32_16x16x32_bf16 v[122:125], v[106:109], v[198:201], v[122:125]
	v_mfma_f32_16x16x32_bf16 v[94:97], v[98:101], v[206:209], v[94:97]
	v_mfma_f32_16x16x32_bf16 v[90:93], v[106:109], v[206:209], v[90:93]
	v_mfma_f32_16x16x32_bf16 v[78:81], v[98:101], v[214:217], v[78:81]
	v_mfma_f32_16x16x32_bf16 v[74:77], v[106:109], v[214:217], v[74:77]
	v_mfma_f32_16x16x32_bf16 v[142:145], v[102:105], v[194:197], v[142:145]
	v_mfma_f32_16x16x32_bf16 v[138:141], v[110:113], v[194:197], v[138:141]
	v_mfma_f32_16x16x32_bf16 v[126:129], v[102:105], v[202:205], v[126:129]
	v_mfma_f32_16x16x32_bf16 v[122:125], v[110:113], v[202:205], v[122:125]
	v_mfma_f32_16x16x32_bf16 v[94:97], v[102:105], v[210:213], v[94:97]
	v_mfma_f32_16x16x32_bf16 v[90:93], v[110:113], v[210:213], v[90:93]
	v_mfma_f32_16x16x32_bf16 v[78:81], v[102:105], v[218:221], v[78:81]
	v_mfma_f32_16x16x32_bf16 v[74:77], v[110:113], v[218:221], v[74:77]
	s_setprio 0
	s_setprio 1
	v_mfma_f32_16x16x32_bf16 v[134:137], v[158:161], v[184:187], v[134:137]
	v_mfma_f32_16x16x32_bf16 v[130:133], v[166:169], v[184:187], v[130:133]
	v_mfma_f32_16x16x32_bf16 v[118:121], v[158:161], v[198:201], v[118:121]
	v_mfma_f32_16x16x32_bf16 v[114:117], v[166:169], v[198:201], v[114:117]
	v_mfma_f32_16x16x32_bf16 v[86:89], v[158:161], v[206:209], v[86:89]
	v_mfma_f32_16x16x32_bf16 v[82:85], v[166:169], v[206:209], v[82:85]
	v_mfma_f32_16x16x32_bf16 v[70:73], v[158:161], v[214:217], v[70:73]
	v_mfma_f32_16x16x32_bf16 v[66:69], v[166:169], v[214:217], v[66:69]
	v_mfma_f32_16x16x32_bf16 v[134:137], v[162:165], v[194:197], v[134:137]
	v_mfma_f32_16x16x32_bf16 v[130:133], v[170:173], v[194:197], v[130:133]
	v_mfma_f32_16x16x32_bf16 v[118:121], v[162:165], v[202:205], v[118:121]
	v_mfma_f32_16x16x32_bf16 v[114:117], v[170:173], v[202:205], v[114:117]
	v_mfma_f32_16x16x32_bf16 v[86:89], v[162:165], v[210:213], v[86:89]
	v_mfma_f32_16x16x32_bf16 v[82:85], v[170:173], v[210:213], v[82:85]
	v_mfma_f32_16x16x32_bf16 v[70:73], v[162:165], v[218:221], v[70:73]
	v_mfma_f32_16x16x32_bf16 v[66:69], v[170:173], v[218:221], v[66:69]
	s_setprio 0
	s_barrier
; #define PG8_STAGE(bufoff, gbase, voff) do { _Pragma("unroll") for (int _i = 0; _i < 2; ++_i) \
;         __builtin_amdgcn_global_load_lds((const unsigned*)((const char*)(gbase) + (voff)[_i]), (PG8_LAS unsigned*)(lds + (bufoff) + ldsw + _i * 8192), 16, 0, 0); } while (0)
; #define PG8_LDA(dst, b, h) do { _Pragma("unroll") for (int m = 0; m < 4; ++m) _Pragma("unroll") for (int k = 0; k < 2; ++k) dst[m][k] = *(const PG8_LAS bf16x8*)(lds + PG8_SA(b, h) + aoff + m * 2048 + k * 1024); } while (0)
; #define PG8_MMA(ai, bj, At, Bt) do { __builtin_amdgcn_s_setprio(1); _Pragma("unroll") for (int m = 0; m < 4; ++m) _Pragma("unroll") for (int n = 0; n < 2; ++n) _Pragma("unroll") for (int k = 0; k < 2; ++k) \
;         acc[ai][bj][m][n] = __builtin_amdgcn_mfma_f32_16x16x32_bf16(Bt[n][k], At[m][k], acc[ai][bj][m][n], 0, 0, 0); __builtin_amdgcn_s_setprio(0); } while (0)
; #define PG8_WAIT_V(n) asm volatile("s_waitcnt vmcnt(" #n ")" ::: "memory")
; #define PG8_WAIT_L(n) asm volatile("s_waitcnt lgkmcnt(" #n ")" ::: "memory")
; #define PG8_BAR __builtin_amdgcn_s_barrier()
; #define PG8_SCHED __builtin_amdgcn_sched_barrier(0)
; template <class Epi, class Sched, bool ALIGN_EPI = false, bool SP2 = false>
; __device__ __forceinline__ void gemm_phase(PG8_LAS unsigned char* lds, const Gemm g, const Sched& S, const Epi& E) {
;     ...
;         for (int t = 0; t < nt; t += 2) {
;     ...
;             PG8_LDA(At, 1, 1); PG8_STAGE(PG8_SB(1, 0), b3, voffB); PG8_STAGE(PG8_SB(1, 1), b3 + hstep, voffB); PG8_STAGE(PG8_SA(1, 0), a3, voffA);
;             PG8_WAIT_V(8); PG8_WAIT_L(0); PG8_BAR; PG8_MMA(1, 0, At, B0); PG8_MMA(1, 1, At, B1); PG8_BAR; PG8_SCHED;
	s_add_i32 s52, s67, s24
	v_lshl_add_u64 v[174:175], v[174:175], 0, s[8:9]
	s_mov_b32 m0, s52
	ds_read_b128 v[184:187], v182 offset:49152
	ds_read_b128 v[194:197], v182 offset:50176
	ds_read_b128 v[198:201], v182 offset:51200
	ds_read_b128 v[202:205], v182 offset:52224
	ds_read_b128 v[206:209], v182 offset:53248
	ds_read_b128 v[210:213], v182 offset:54272
	ds_read_b128 v[214:217], v182 offset:55296
	ds_read_b128 v[218:221], v182 offset:56320
	global_load_lds_dwordx4 v[174:175], off
	s_add_i32 m0, s52, 0x2000
	s_add_u32 s36, s36, 0x40080
	v_lshl_add_u64 v[174:175], v[178:179], 0, s[8:9]
	s_addc_u32 s37, s37, 0
	s_add_i32 s52, s68, s24
	global_load_lds_dwordx4 v[174:175], off
	v_lshl_add_u64 v[174:175], s[36:37], 0, v[0:1]
	s_mov_b32 m0, s52
	s_nop 0
	global_load_lds_dwordx4 v[174:175], off
	v_lshl_add_u64 v[174:175], s[36:37], 0, v[150:151]
	s_add_i32 m0, s52, 0x2000
	s_nop 0
	global_load_lds_dwordx4 v[174:175], off
	v_lshl_add_u64 v[174:175], v[188:189], 0, s[8:9]
	s_mov_b32 m0, s64
	s_nop 0
	global_load_lds_dwordx4 v[174:175], off
	v_lshl_add_u64 v[174:175], v[222:223], 0, s[8:9]
	s_mov_b32 m0, s65
	s_nop 0
	global_load_lds_dwordx4 v[174:175], off
	s_waitcnt vmcnt(8)
	s_waitcnt lgkmcnt(0)
	s_barrier
	s_setprio 1
	s_waitcnt lgkmcnt(0)
	v_mfma_f32_16x16x32_bf16 v[62:65], v[98:101], v[184:187], v[62:65]
	v_mfma_f32_16x16x32_bf16 v[58:61], v[106:109], v[184:187], v[58:61]
	v_mfma_f32_16x16x32_bf16 v[46:49], v[98:101], v[198:201], v[46:49]
	v_mfma_f32_16x16x32_bf16 v[42:45], v[106:109], v[198:201], v[42:45]
	v_mfma_f32_16x16x32_bf16 v[30:33], v[98:101], v[206:209], v[30:33]
	v_mfma_f32_16x16x32_bf16 v[26:29], v[106:109], v[206:209], v[26:29]
	v_mfma_f32_16x16x32_bf16 v[14:17], v[98:101], v[214:217], v[14:17]
	v_mfma_f32_16x16x32_bf16 v[10:13], v[106:109], v[214:217], v[10:13]
	v_mfma_f32_16x16x32_bf16 v[62:65], v[102:105], v[194:197], v[62:65]
	v_mfma_f32_16x16x32_bf16 v[58:61], v[110:113], v[194:197], v[58:61]
	v_mfma_f32_16x16x32_bf16 v[46:49], v[102:105], v[202:205], v[46:49]
	v_mfma_f32_16x16x32_bf16 v[42:45], v[110:113], v[202:205], v[42:45]
	v_mfma_f32_16x16x32_bf16 v[30:33], v[102:105], v[210:213], v[30:33]
	v_mfma_f32_16x16x32_bf16 v[26:29], v[110:113], v[210:213], v[26:29]
	v_mfma_f32_16x16x32_bf16 v[14:17], v[102:105], v[218:221], v[14:17]
	v_mfma_f32_16x16x32_bf16 v[10:13], v[110:113], v[218:221], v[10:13]
	s_setprio 0
	s_setprio 1
	v_mfma_f32_16x16x32_bf16 v[54:57], v[158:161], v[184:187], v[54:57]
	v_mfma_f32_16x16x32_bf16 v[50:53], v[166:169], v[184:187], v[50:53]
	v_mfma_f32_16x16x32_bf16 v[38:41], v[158:161], v[198:201], v[38:41]
	v_mfma_f32_16x16x32_bf16 v[34:37], v[166:169], v[198:201], v[34:37]
	v_mfma_f32_16x16x32_bf16 v[22:25], v[158:161], v[206:209], v[22:25]
	v_mfma_f32_16x16x32_bf16 v[18:21], v[166:169], v[206:209], v[18:21]
	v_mfma_f32_16x16x32_bf16 v[6:9], v[158:161], v[214:217], v[6:9]
	v_mfma_f32_16x16x32_bf16 v[2:5], v[166:169], v[214:217], v[2:5]
	v_mfma_f32_16x16x32_bf16 v[54:57], v[162:165], v[194:197], v[54:57]
	v_mfma_f32_16x16x32_bf16 v[50:53], v[170:173], v[194:197], v[50:53]
	v_mfma_f32_16x16x32_bf16 v[38:41], v[162:165], v[202:205], v[38:41]
	v_mfma_f32_16x16x32_bf16 v[34:37], v[170:173], v[202:205], v[34:37]
	v_mfma_f32_16x16x32_bf16 v[22:25], v[162:165], v[210:213], v[22:25]
	v_mfma_f32_16x16x32_bf16 v[18:21], v[170:173], v[210:213], v[18:21]
	v_mfma_f32_16x16x32_bf16 v[6:9], v[162:165], v[218:221], v[6:9]
	v_mfma_f32_16x16x32_bf16 v[2:5], v[170:173], v[218:221], v[2:5]
	s_setprio 0
	s_barrier
	s_add_i32 s51, s51, 2
	s_add_u32 s18, s18, 0x100
	s_addc_u32 s19, s19, 0
	s_add_u32 s35, s35, 0x100
	s_addc_u32 s49, s49, 0
	s_cmp_gt_u32 s51, 13

; template <class Epi, class Sched, bool ALIGN_EPI = false, bool SP2 = false>
; __device__ __forceinline__ void gemm_phase(PG8_LAS unsigned char* lds, const Gemm g, const Sched& S, const Epi& E) {
;     ...
;         const bool has_next = S.next(ui + 1, nxt);
;         const char* nA = has_next ? (const char*)g.A + (size_t)nxt.pm * tstep : cA; const char* nB = has_next ? (const char*)g.Bt + (size_t)nxt.pn * tstep : cB;
;     ...
; #pragma unroll
;         for (int a = 0; a < 2; ++a)
; #pragma unroll
;             for (int b = 0; b < 2; ++b)
; #pragma unroll
;                 for (int m = 0; m < 4; ++m)
; #pragma unroll
;                     for (int n = 0; n < 2; ++n) acc[a][b][m][n] = (f32x4){0.f, 0.f, 0.f, 0.f};
.LBB0_290:
	s_ashr_i32 s45, s44, 31
	s_lshl_b64 s[30:31], s[44:45], 19
	s_add_u32 s50, s25, s30
	s_addc_u32 s51, s26, s31
	s_and_b64 s[30:31], s[48:49], exec
	s_cselect_b32 s30, s51, s19
	s_cselect_b32 s31, s50, s18
	s_ashr_i32 s43, s42, 31
	s_lshl_b64 s[34:35], s[42:43], 19
	s_add_u32 s54, s96, s34
	s_addc_u32 s55, s97, s35
	s_and_b64 s[34:35], s[48:49], exec
	s_cselect_b32 s34, s55, s59
	s_cselect_b32 s35, s54, s58
	s_add_u32 s18, s18, 0x40080
	s_addc_u32 s19, s19, 0
	s_add_u32 s43, s58, 0x100

; template <class Epi, class Sched, bool ALIGN_EPI = false, bool SP2 = false>
; __device__ __forceinline__ void gemm_phase(PG8_LAS unsigned char* lds, const Gemm g, const Sched& S, const Epi& E) {
;     ...
;         for (int t = 0; t < nt; t += 2) {
;     ...
; #pragma unroll
;         for (int a = 0; a < 2; ++a)
; #pragma unroll
;             for (int b = 0; b < 2; ++b)
; #pragma unroll
;                 for (int m = 0; m < 4; ++m)
; #pragma unroll
;                     for (int n = 0; n < 2; ++n) acc[a][b][m][n] = (f32x4){0.f, 0.f, 0.f, 0.f};
	s_addc_u32 s45, s59, 0
	s_mov_b32 s52, -2


; template <class Epi, class Sched, bool ALIGN_EPI = false, bool SP2 = false>
; __device__ __forceinline__ void gemm_phase(PG8_LAS unsigned char* lds, const Gemm g, const Sched& S, const Epi& E) {
;     ...
; #pragma unroll
;         for (int a = 0; a < 2; ++a)
; #pragma unroll
;             for (int b = 0; b < 2; ++b)
; #pragma unroll
;                 for (int m = 0; m < 4; ++m)
; #pragma unroll
;                     for (int n = 0; n < 2; ++n) acc[a][b][m][n] = (f32x4){0.f, 0.f, 0.f, 0.f};
	s_waitcnt vmcnt(0)


; #define PG8_STAGE(bufoff, gbase, voff) do { _Pragma("unroll") for (int _i = 0; _i < 2; ++_i) \
;         __builtin_amdgcn_global_load_lds((const unsigned*)((const char*)(gbase) + (voff)[_i]), (PG8_LAS unsigned*)(lds + (bufoff) + ldsw + _i * 8192), 16, 0, 0); } while (0)
; #define PG8_LDA(dst, b, h) do { _Pragma("unroll") for (int m = 0; m < 4; ++m) _Pragma("unroll") for (int k = 0; k < 2; ++k) dst[m][k] = *(const PG8_LAS bf16x8*)(lds + PG8_SA(b, h) + aoff + m * 2048 + k * 1024); } while (0)
; #define PG8_LDB(dst, b, h) do { _Pragma("unroll") for (int n = 0; n < 2; ++n) _Pragma("unroll") for (int k = 0; k < 2; ++k) dst[n][k] = *(const PG8_LAS bf16x8*)(lds + PG8_SB(b, h) + boff + n * 2048 + k * 1024); } while (0)
; #define PG8_MMA(ai, bj, At, Bt) do { __builtin_amdgcn_s_setprio(1); _Pragma("unroll") for (int m = 0; m < 4; ++m) _Pragma("unroll") for (int n = 0; n < 2; ++n) _Pragma("unroll") for (int k = 0; k < 2; ++k) \
;         acc[ai][bj][m][n] = __builtin_amdgcn_mfma_f32_16x16x32_bf16(Bt[n][k], At[m][k], acc[ai][bj][m][n], 0, 0, 0); __builtin_amdgcn_s_setprio(0); } while (0)
; #define PG8_WAIT_V(n) asm volatile("s_waitcnt vmcnt(" #n ")" ::: "memory")
; #define PG8_WAIT_L(n) asm volatile("s_waitcnt lgkmcnt(" #n ")" ::: "memory")
; #define PG8_BAR __builtin_amdgcn_s_barrier()
; #define PG8_SCHED __builtin_amdgcn_sched_barrier(0)
; template <class Epi, class Sched, bool ALIGN_EPI = false, bool SP2 = false>
; __device__ __forceinline__ void gemm_phase(PG8_LAS unsigned char* lds, const Gemm g, const Sched& S, const Epi& E) {
;     ...
;             const bool last = (t == nt - 2);
;             const char* a1 = cA + (size_t)(t + 1) * kstep;
;             const char* a2 = last ? nA : cA + (size_t)(t + 2) * kstep; const char* b2 = last ? nB : cB + (size_t)(t + 2) * kstep;
;             const char* a3 = a2 + kstep; const char* b3 = b2 + kstep;
;             if (last && has_next) S.a_ready(nxt);
;             if constexpr (SP2) {
;             PG8_LDB(B0, 0, 0); PG8_LDB(B1, 0, 1); PG8_SCHED; PG8_LDA(At, 0, 0); PG8_STAGE(PG8_SA(1, 1), a1 + hstep, voffA);
;             PG8_WAIT_V(8); PG8_WAIT_L(0); PG8_BAR; PG8_MMA(0, 0, At, B0); PG8_MMA(0, 1, At, B1); PG8_BAR; PG8_SCHED;
;             PG8_LDA(At, 0, 1); PG8_STAGE(PG8_SB(0, 0), b2, voffB); PG8_STAGE(PG8_SB(0, 1), b2 + hstep, voffB); PG8_STAGE(PG8_SA(0, 0), a2, voffA);
	s_add_u32 s53, s18, 0xfffc0080
	s_addc_u32 s58, s19, -1
	s_add_i32 s64, 0, 0x10000
	s_cmp_eq_u32 s52, 12
	s_cselect_b32 s61, s30, s58
	s_cselect_b32 s60, s31, s53
	s_cselect_b32 s59, s34, s45
	s_cselect_b32 s58, s35, s43
	s_add_i32 s53, 0, 0x14000
	v_add_u32_e32 v142, s64, v167
	v_add_u32_e32 v164, s53, v167
	ds_read_b128 v[130:133], v142
	ds_read_b128 v[134:137], v142 offset:1024
	ds_read_b128 v[138:141], v142 offset:2048
	ds_read_b128 v[142:145], v142 offset:3072
	ds_read_b128 v[156:159], v164
	ds_read_b128 v[160:163], v164 offset:1024
	ds_read_b128 v[170:173], v164 offset:2048
	ds_read_b128 v[174:177], v164 offset:3072
	v_lshl_add_u64 v[164:165], s[18:19], 0, v[152:153]
	s_add_i32 m0, s27, 0xc000
	ds_read_b128 v[178:181], v169
	ds_read_b128 v[182:185], v169 offset:1024
	ds_read_b128 v[186:189], v169 offset:2048
	ds_read_b128 v[194:197], v169 offset:3072
	ds_read_b128 v[198:201], v169 offset:4096
	ds_read_b128 v[202:205], v169 offset:5120
	ds_read_b128 v[206:209], v169 offset:6144
	ds_read_b128 v[210:213], v169 offset:7168
	global_load_lds_dwordx4 v[164:165], off
	v_lshl_add_u64 v[164:165], s[18:19], 0, v[154:155]
	s_add_i32 m0, s27, 0xe000
	s_nop 0
	global_load_lds_dwordx4 v[164:165], off
	s_waitcnt vmcnt(8)
	s_waitcnt lgkmcnt(0)
	s_barrier
	s_setprio 1
	s_waitcnt lgkmcnt(0)
	v_mfma_f32_16x16x32_bf16 v[126:129], v[130:133], v[178:181], 0
	v_mfma_f32_16x16x32_bf16 v[122:125], v[138:141], v[178:181], 0
	v_mfma_f32_16x16x32_bf16 v[114:117], v[130:133], v[186:189], 0
	v_mfma_f32_16x16x32_bf16 v[110:113], v[138:141], v[186:189], 0
	v_mfma_f32_16x16x32_bf16 v[102:105], v[130:133], v[198:201], 0
	v_mfma_f32_16x16x32_bf16 v[94:97], v[138:141], v[198:201], 0
	v_mfma_f32_16x16x32_bf16 v[86:89], v[130:133], v[206:209], 0
	v_mfma_f32_16x16x32_bf16 v[78:81], v[138:141], v[206:209], 0
	v_mfma_f32_16x16x32_bf16 v[126:129], v[134:137], v[182:185], v[126:129]
	v_mfma_f32_16x16x32_bf16 v[122:125], v[142:145], v[182:185], v[122:125]
	v_mfma_f32_16x16x32_bf16 v[114:117], v[134:137], v[194:197], v[114:117]
	v_mfma_f32_16x16x32_bf16 v[110:113], v[142:145], v[194:197], v[110:113]
	v_mfma_f32_16x16x32_bf16 v[102:105], v[134:137], v[202:205], v[102:105]
	v_mfma_f32_16x16x32_bf16 v[94:97], v[142:145], v[202:205], v[94:97]
	v_mfma_f32_16x16x32_bf16 v[86:89], v[134:137], v[210:213], v[86:89]
	v_mfma_f32_16x16x32_bf16 v[78:81], v[142:145], v[210:213], v[78:81]
	s_setprio 0
	s_setprio 1
	v_mfma_f32_16x16x32_bf16 v[118:121], v[156:159], v[178:181], 0
	v_mfma_f32_16x16x32_bf16 v[106:109], v[170:173], v[178:181], 0
	v_mfma_f32_16x16x32_bf16 v[98:101], v[156:159], v[186:189], 0
	v_mfma_f32_16x16x32_bf16 v[90:93], v[170:173], v[186:189], 0
	v_mfma_f32_16x16x32_bf16 v[82:85], v[156:159], v[198:201], 0
	v_mfma_f32_16x16x32_bf16 v[74:77], v[170:173], v[198:201], 0
	v_mfma_f32_16x16x32_bf16 v[70:73], v[156:159], v[206:209], 0
	v_mfma_f32_16x16x32_bf16 v[66:69], v[170:173], v[206:209], 0
	v_mfma_f32_16x16x32_bf16 v[118:121], v[160:163], v[182:185], v[118:121]
	v_mfma_f32_16x16x32_bf16 v[106:109], v[174:177], v[182:185], v[106:109]
	v_mfma_f32_16x16x32_bf16 v[98:101], v[160:163], v[194:197], v[98:101]
	v_mfma_f32_16x16x32_bf16 v[90:93], v[174:177], v[194:197], v[90:93]
	v_mfma_f32_16x16x32_bf16 v[82:85], v[160:163], v[202:205], v[82:85]
	v_mfma_f32_16x16x32_bf16 v[74:77], v[174:177], v[202:205], v[74:77]
	v_mfma_f32_16x16x32_bf16 v[70:73], v[160:163], v[210:213], v[70:73]
	v_mfma_f32_16x16x32_bf16 v[66:69], v[174:177], v[210:213], v[66:69]
	s_setprio 0
	s_barrier
	s_add_i32 s64, s64, s24
	v_lshl_add_u64 v[164:165], s[58:59], 0, v[0:1]
	s_mov_b32 m0, s64
	ds_read_b128 v[178:181], v169 offset:16384
	ds_read_b128 v[182:185], v169 offset:17408
	ds_read_b128 v[186:189], v169 offset:18432
	ds_read_b128 v[194:197], v169 offset:19456
	ds_read_b128 v[198:201], v169 offset:20480
	ds_read_b128 v[202:205], v169 offset:21504
	ds_read_b128 v[206:209], v169 offset:22528
	ds_read_b128 v[210:213], v169 offset:23552
	global_load_lds_dwordx4 v[164:165], off
	s_add_i32 m0, s64, 0x2000
	s_add_u32 s64, s58, 0x40000
	v_lshl_add_u64 v[214:215], s[58:59], 0, v[150:151]
	s_addc_u32 s65, s59, 0
	s_add_i32 s53, s53, s24
	global_load_lds_dwordx4 v[214:215], off
	v_lshl_add_u64 v[216:217], s[64:65], 0, v[0:1]
	s_mov_b32 m0, s53
	v_lshl_add_u64 v[218:219], s[60:61], 0, v[148:149]
	global_load_lds_dwordx4 v[216:217], off
	v_lshl_add_u64 v[216:217], s[64:65], 0, v[150:151]
	s_add_i32 m0, s53, 0x2000
	s_nop 0
	global_load_lds_dwordx4 v[216:217], off
	v_lshl_add_u64 v[216:217], s[60:61], 0, v[146:147]
	s_mov_b32 m0, s27
	s_nop 0
	global_load_lds_dwordx4 v[216:217], off
	s_mov_b32 m0, s28
	s_nop 0
	global_load_lds_dwordx4 v[218:219], off
	s_waitcnt vmcnt(8)
	s_waitcnt lgkmcnt(0)
	s_barrier
; #define PG8_STAGE(bufoff, gbase, voff) do { _Pragma("unroll") for (int _i = 0; _i < 2; ++_i) \
;         __builtin_amdgcn_global_load_lds((const unsigned*)((const char*)(gbase) + (voff)[_i]), (PG8_LAS unsigned*)(lds + (bufoff) + ldsw + _i * 8192), 16, 0, 0); } while (0)
; #define PG8_LDA(dst, b, h) do { _Pragma("unroll") for (int m = 0; m < 4; ++m) _Pragma("unroll") for (int k = 0; k < 2; ++k) dst[m][k] = *(const PG8_LAS bf16x8*)(lds + PG8_SA(b, h) + aoff + m * 2048 + k * 1024); } while (0)
; #define PG8_LDB(dst, b, h) do { _Pragma("unroll") for (int n = 0; n < 2; ++n) _Pragma("unroll") for (int k = 0; k < 2; ++k) dst[n][k] = *(const PG8_LAS bf16x8*)(lds + PG8_SB(b, h) + boff + n * 2048 + k * 1024); } while (0)
; #define PG8_MMA(ai, bj, At, Bt) do { __builtin_amdgcn_s_setprio(1); _Pragma("unroll") for (int m = 0; m < 4; ++m) _Pragma("unroll") for (int n = 0; n < 2; ++n) _Pragma("unroll") for (int k = 0; k < 2; ++k) \
;         acc[ai][bj][m][n] = __builtin_amdgcn_mfma_f32_16x16x32_bf16(Bt[n][k], At[m][k], acc[ai][bj][m][n], 0, 0, 0); __builtin_amdgcn_s_setprio(0); } while (0)
; #define PG8_WAIT_V(n) asm volatile("s_waitcnt vmcnt(" #n ")" ::: "memory")
; #define PG8_WAIT_L(n) asm volatile("s_waitcnt lgkmcnt(" #n ")" ::: "memory")
; #define PG8_BAR __builtin_amdgcn_s_barrier()
; #define PG8_SCHED __builtin_amdgcn_sched_barrier(0)
; template <class Epi, class Sched, bool ALIGN_EPI = false, bool SP2 = false>
; __device__ __forceinline__ void gemm_phase(PG8_LAS unsigned char* lds, const Gemm g, const Sched& S, const Epi& E) {
;     ...
;             PG8_WAIT_V(8); PG8_WAIT_L(0); PG8_BAR; PG8_MMA(1, 0, At, B0); PG8_MMA(1, 1, At, B1); PG8_BAR; PG8_SCHED;
;             PG8_LDB(B0, 1, 0); PG8_LDB(B1, 1, 1); PG8_SCHED; PG8_LDA(At, 1, 0); PG8_STAGE(PG8_SA(0, 1), a2 + hstep, voffA);
;             PG8_WAIT_V(8); PG8_WAIT_L(0); PG8_BAR; PG8_MMA(0, 0, At, B0); PG8_MMA(0, 1, At, B1); PG8_BAR; PG8_SCHED;
	s_setprio 1
	s_waitcnt lgkmcnt(0)
	v_mfma_f32_16x16x32_bf16 v[62:65], v[130:133], v[178:181], 0
	v_mfma_f32_16x16x32_bf16 v[58:61], v[138:141], v[178:181], 0
	v_mfma_f32_16x16x32_bf16 v[54:57], v[130:133], v[186:189], 0
	v_mfma_f32_16x16x32_bf16 v[46:49], v[138:141], v[186:189], 0
	v_mfma_f32_16x16x32_bf16 v[38:41], v[130:133], v[198:201], 0
	v_mfma_f32_16x16x32_bf16 v[30:33], v[138:141], v[198:201], 0
	v_mfma_f32_16x16x32_bf16 v[22:25], v[130:133], v[206:209], 0
	v_mfma_f32_16x16x32_bf16 v[14:17], v[138:141], v[206:209], 0
	v_mfma_f32_16x16x32_bf16 v[62:65], v[134:137], v[182:185], v[62:65]
	v_mfma_f32_16x16x32_bf16 v[58:61], v[142:145], v[182:185], v[58:61]
	v_mfma_f32_16x16x32_bf16 v[54:57], v[134:137], v[194:197], v[54:57]
	v_mfma_f32_16x16x32_bf16 v[46:49], v[142:145], v[194:197], v[46:49]
	v_mfma_f32_16x16x32_bf16 v[38:41], v[134:137], v[202:205], v[38:41]
	v_mfma_f32_16x16x32_bf16 v[30:33], v[142:145], v[202:205], v[30:33]
	v_mfma_f32_16x16x32_bf16 v[22:25], v[134:137], v[210:213], v[22:25]
	v_mfma_f32_16x16x32_bf16 v[14:17], v[142:145], v[210:213], v[14:17]
	s_setprio 0
	s_setprio 1
	v_mfma_f32_16x16x32_bf16 v[50:53], v[156:159], v[178:181], 0
	v_mfma_f32_16x16x32_bf16 v[42:45], v[170:173], v[178:181], 0
	v_mfma_f32_16x16x32_bf16 v[34:37], v[156:159], v[186:189], 0
	v_mfma_f32_16x16x32_bf16 v[26:29], v[170:173], v[186:189], 0
	v_mfma_f32_16x16x32_bf16 v[18:21], v[156:159], v[198:201], 0
	v_mfma_f32_16x16x32_bf16 v[10:13], v[170:173], v[198:201], 0
	v_mfma_f32_16x16x32_bf16 v[6:9], v[156:159], v[206:209], 0
	v_mfma_f32_16x16x32_bf16 v[2:5], v[170:173], v[206:209], 0
	v_mfma_f32_16x16x32_bf16 v[50:53], v[160:163], v[182:185], v[50:53]
	v_mfma_f32_16x16x32_bf16 v[42:45], v[174:177], v[182:185], v[42:45]
	v_mfma_f32_16x16x32_bf16 v[34:37], v[160:163], v[194:197], v[34:37]
	v_mfma_f32_16x16x32_bf16 v[26:29], v[174:177], v[194:197], v[26:29]
	v_mfma_f32_16x16x32_bf16 v[18:21], v[160:163], v[202:205], v[18:21]
	v_mfma_f32_16x16x32_bf16 v[10:13], v[174:177], v[202:205], v[10:13]
	v_mfma_f32_16x16x32_bf16 v[6:9], v[160:163], v[210:213], v[6:9]
	v_mfma_f32_16x16x32_bf16 v[2:5], v[174:177], v[210:213], v[2:5]
	s_setprio 0
	s_barrier
	s_add_i32 s53, 0, 0x18000
	s_add_i32 s64, 0, 0x1c000
	v_add_u32_e32 v142, s53, v167
	v_add_u32_e32 v174, s64, v167
	ds_read_b128 v[130:133], v142
	ds_read_b128 v[134:137], v142 offset:1024
	ds_read_b128 v[138:141], v142 offset:2048
	ds_read_b128 v[142:145], v142 offset:3072
	ds_read_b128 v[156:159], v174
	ds_read_b128 v[160:163], v174 offset:1024
	ds_read_b128 v[170:173], v174 offset:2048
	ds_read_b128 v[174:177], v174 offset:3072
	s_add_u32 s60, s60, 0x40000
	s_addc_u32 s61, s61, 0
	s_mov_b32 m0, s29
	v_lshl_add_u64 v[220:221], s[60:61], 0, v[146:147]
	ds_read_b128 v[178:181], v169 offset:32768
	ds_read_b128 v[182:185], v169 offset:33792
	ds_read_b128 v[186:189], v169 offset:34816
	ds_read_b128 v[194:197], v169 offset:35840
	ds_read_b128 v[198:201], v169 offset:36864
	ds_read_b128 v[202:205], v169 offset:37888
	ds_read_b128 v[206:209], v169 offset:38912
	ds_read_b128 v[210:213], v169 offset:39936
	global_load_lds_dwordx4 v[220:221], off
	v_lshl_add_u64 v[220:221], s[60:61], 0, v[148:149]
	s_mov_b32 m0, s47
	s_nop 0
	global_load_lds_dwordx4 v[220:221], off
	s_waitcnt vmcnt(8)
	s_waitcnt lgkmcnt(0)
	s_barrier
	s_setprio 1
	s_waitcnt lgkmcnt(0)
	v_mfma_f32_16x16x32_bf16 v[126:129], v[130:133], v[178:181], v[126:129]
	v_mfma_f32_16x16x32_bf16 v[122:125], v[138:141], v[178:181], v[122:125]
	v_mfma_f32_16x16x32_bf16 v[114:117], v[130:133], v[186:189], v[114:117]
	v_mfma_f32_16x16x32_bf16 v[110:113], v[138:141], v[186:189], v[110:113]
	v_mfma_f32_16x16x32_bf16 v[102:105], v[130:133], v[198:201], v[102:105]
	v_mfma_f32_16x16x32_bf16 v[94:97], v[138:141], v[198:201], v[94:97]
	v_mfma_f32_16x16x32_bf16 v[86:89], v[130:133], v[206:209], v[86:89]
	v_mfma_f32_16x16x32_bf16 v[78:81], v[138:141], v[206:209], v[78:81]
	v_mfma_f32_16x16x32_bf16 v[126:129], v[134:137], v[182:185], v[126:129]
	v_mfma_f32_16x16x32_bf16 v[122:125], v[142:145], v[182:185], v[122:125]
	v_mfma_f32_16x16x32_bf16 v[114:117], v[134:137], v[194:197], v[114:117]
	v_mfma_f32_16x16x32_bf16 v[110:113], v[142:145], v[194:197], v[110:113]
	v_mfma_f32_16x16x32_bf16 v[102:105], v[134:137], v[202:205], v[102:105]
	v_mfma_f32_16x16x32_bf16 v[94:97], v[142:145], v[202:205], v[94:97]
	v_mfma_f32_16x16x32_bf16 v[86:89], v[134:137], v[210:213], v[86:89]
	v_mfma_f32_16x16x32_bf16 v[78:81], v[142:145], v[210:213], v[78:81]
	s_setprio 0
	s_setprio 1
	v_mfma_f32_16x16x32_bf16 v[118:121], v[156:159], v[178:181], v[118:121]
	v_mfma_f32_16x16x32_bf16 v[106:109], v[170:173], v[178:181], v[106:109]
	v_mfma_f32_16x16x32_bf16 v[98:101], v[156:159], v[186:189], v[98:101]
	v_mfma_f32_16x16x32_bf16 v[90:93], v[170:173], v[186:189], v[90:93]
	v_mfma_f32_16x16x32_bf16 v[82:85], v[156:159], v[198:201], v[82:85]
	v_mfma_f32_16x16x32_bf16 v[74:77], v[170:173], v[198:201], v[74:77]
	v_mfma_f32_16x16x32_bf16 v[70:73], v[156:159], v[206:209], v[70:73]
	v_mfma_f32_16x16x32_bf16 v[66:69], v[170:173], v[206:209], v[66:69]
	v_mfma_f32_16x16x32_bf16 v[118:121], v[160:163], v[182:185], v[118:121]
	v_mfma_f32_16x16x32_bf16 v[106:109], v[174:177], v[182:185], v[106:109]
	v_mfma_f32_16x16x32_bf16 v[98:101], v[160:163], v[194:197], v[98:101]
	v_mfma_f32_16x16x32_bf16 v[90:93], v[174:177], v[194:197], v[90:93]
	v_mfma_f32_16x16x32_bf16 v[82:85], v[160:163], v[202:205], v[82:85]
	v_mfma_f32_16x16x32_bf16 v[74:77], v[174:177], v[202:205], v[74:77]
	v_mfma_f32_16x16x32_bf16 v[70:73], v[160:163], v[210:213], v[70:73]
	v_mfma_f32_16x16x32_bf16 v[66:69], v[174:177], v[210:213], v[66:69]
	s_setprio 0
	s_barrier
; #define PG8_STAGE(bufoff, gbase, voff) do { _Pragma("unroll") for (int _i = 0; _i < 2; ++_i) \
;         __builtin_amdgcn_global_load_lds((const unsigned*)((const char*)(gbase) + (voff)[_i]), (PG8_LAS unsigned*)(lds + (bufoff) + ldsw + _i * 8192), 16, 0, 0); } while (0)
; #define PG8_LDA(dst, b, h) do { _Pragma("unroll") for (int m = 0; m < 4; ++m) _Pragma("unroll") for (int k = 0; k < 2; ++k) dst[m][k] = *(const PG8_LAS bf16x8*)(lds + PG8_SA(b, h) + aoff + m * 2048 + k * 1024); } while (0)
; #define PG8_MMA(ai, bj, At, Bt) do { __builtin_amdgcn_s_setprio(1); _Pragma("unroll") for (int m = 0; m < 4; ++m) _Pragma("unroll") for (int n = 0; n < 2; ++n) _Pragma("unroll") for (int k = 0; k < 2; ++k) \
;         acc[ai][bj][m][n] = __builtin_amdgcn_mfma_f32_16x16x32_bf16(Bt[n][k], At[m][k], acc[ai][bj][m][n], 0, 0, 0); __builtin_amdgcn_s_setprio(0); } while (0)
; #define PG8_WAIT_V(n) asm volatile("s_waitcnt vmcnt(" #n ")" ::: "memory")
; #define PG8_WAIT_L(n) asm volatile("s_waitcnt lgkmcnt(" #n ")" ::: "memory")
; #define PG8_BAR __builtin_amdgcn_s_barrier()
; #define PG8_SCHED __builtin_amdgcn_sched_barrier(0)
; template <class Epi, class Sched, bool ALIGN_EPI = false, bool SP2 = false>
; __device__ __forceinline__ void gemm_phase(PG8_LAS unsigned char* lds, const Gemm g, const Sched& S, const Epi& E) {
;     ...
;         for (int t = 0; t < nt; t += 2) {
;     ...
;             PG8_LDA(At, 1, 1); PG8_STAGE(PG8_SB(1, 0), b3, voffB); PG8_STAGE(PG8_SB(1, 1), b3 + hstep, voffB); PG8_STAGE(PG8_SA(1, 0), a3, voffA);
;             PG8_WAIT_V(8); PG8_WAIT_L(0); PG8_BAR; PG8_MMA(1, 0, At, B0); PG8_MMA(1, 1, At, B1); PG8_BAR; PG8_SCHED;
	s_add_i32 s53, s53, s24
	v_lshl_add_u64 v[164:165], v[164:165], 0, s[8:9]
	s_mov_b32 m0, s53
	ds_read_b128 v[178:181], v169 offset:49152
	ds_read_b128 v[182:185], v169 offset:50176
	ds_read_b128 v[186:189], v169 offset:51200
	ds_read_b128 v[194:197], v169 offset:52224
	ds_read_b128 v[198:201], v169 offset:53248
	ds_read_b128 v[202:205], v169 offset:54272
	ds_read_b128 v[206:209], v169 offset:55296
	ds_read_b128 v[210:213], v169 offset:56320
	global_load_lds_dwordx4 v[164:165], off
	s_add_i32 m0, s53, 0x2000
	s_add_u32 s58, s58, 0x40080
	v_lshl_add_u64 v[164:165], v[214:215], 0, s[8:9]
	s_addc_u32 s59, s59, 0
	s_add_i32 s53, s64, s24
	global_load_lds_dwordx4 v[164:165], off
	v_lshl_add_u64 v[164:165], s[58:59], 0, v[0:1]
	s_mov_b32 m0, s53
	s_nop 0
	global_load_lds_dwordx4 v[164:165], off
	v_lshl_add_u64 v[164:165], s[58:59], 0, v[150:151]
	s_add_i32 m0, s53, 0x2000
	s_nop 0
	global_load_lds_dwordx4 v[164:165], off
	v_lshl_add_u64 v[164:165], v[216:217], 0, s[8:9]
	s_mov_b32 m0, s57
	s_nop 0
	global_load_lds_dwordx4 v[164:165], off
	v_lshl_add_u64 v[164:165], v[218:219], 0, s[8:9]
	s_mov_b32 m0, s62
	s_nop 0
	global_load_lds_dwordx4 v[164:165], off
	s_waitcnt vmcnt(8)
	s_waitcnt lgkmcnt(0)
	s_barrier
	s_setprio 1
	s_waitcnt lgkmcnt(0)
	v_mfma_f32_16x16x32_bf16 v[62:65], v[130:133], v[178:181], v[62:65]
	v_mfma_f32_16x16x32_bf16 v[58:61], v[138:141], v[178:181], v[58:61]
	v_mfma_f32_16x16x32_bf16 v[54:57], v[130:133], v[186:189], v[54:57]
	v_mfma_f32_16x16x32_bf16 v[46:49], v[138:141], v[186:189], v[46:49]
	v_mfma_f32_16x16x32_bf16 v[38:41], v[130:133], v[198:201], v[38:41]
	v_mfma_f32_16x16x32_bf16 v[30:33], v[138:141], v[198:201], v[30:33]
	v_mfma_f32_16x16x32_bf16 v[22:25], v[130:133], v[206:209], v[22:25]
	v_mfma_f32_16x16x32_bf16 v[14:17], v[138:141], v[206:209], v[14:17]
	v_mfma_f32_16x16x32_bf16 v[62:65], v[134:137], v[182:185], v[62:65]
	v_mfma_f32_16x16x32_bf16 v[58:61], v[142:145], v[182:185], v[58:61]
	v_mfma_f32_16x16x32_bf16 v[54:57], v[134:137], v[194:197], v[54:57]
	v_mfma_f32_16x16x32_bf16 v[46:49], v[142:145], v[194:197], v[46:49]
	v_mfma_f32_16x16x32_bf16 v[38:41], v[134:137], v[202:205], v[38:41]
	v_mfma_f32_16x16x32_bf16 v[30:33], v[142:145], v[202:205], v[30:33]
	v_mfma_f32_16x16x32_bf16 v[22:25], v[134:137], v[210:213], v[22:25]
	v_mfma_f32_16x16x32_bf16 v[14:17], v[142:145], v[210:213], v[14:17]
	s_setprio 0
	s_setprio 1
	v_mfma_f32_16x16x32_bf16 v[50:53], v[156:159], v[178:181], v[50:53]
	v_mfma_f32_16x16x32_bf16 v[42:45], v[170:173], v[178:181], v[42:45]
	v_mfma_f32_16x16x32_bf16 v[34:37], v[156:159], v[186:189], v[34:37]
	v_mfma_f32_16x16x32_bf16 v[26:29], v[170:173], v[186:189], v[26:29]
	v_mfma_f32_16x16x32_bf16 v[18:21], v[156:159], v[198:201], v[18:21]
	v_mfma_f32_16x16x32_bf16 v[10:13], v[170:173], v[198:201], v[10:13]
	v_mfma_f32_16x16x32_bf16 v[6:9], v[156:159], v[206:209], v[6:9]
	v_mfma_f32_16x16x32_bf16 v[2:5], v[170:173], v[206:209], v[2:5]
	v_mfma_f32_16x16x32_bf16 v[50:53], v[160:163], v[182:185], v[50:53]
	v_mfma_f32_16x16x32_bf16 v[42:45], v[174:177], v[182:185], v[42:45]
	v_mfma_f32_16x16x32_bf16 v[34:37], v[160:163], v[194:197], v[34:37]
	v_mfma_f32_16x16x32_bf16 v[26:29], v[174:177], v[194:197], v[26:29]
	v_mfma_f32_16x16x32_bf16 v[18:21], v[160:163], v[202:205], v[18:21]
	v_mfma_f32_16x16x32_bf16 v[10:13], v[174:177], v[202:205], v[10:13]
	v_mfma_f32_16x16x32_bf16 v[6:9], v[160:163], v[210:213], v[6:9]
	v_mfma_f32_16x16x32_bf16 v[2:5], v[174:177], v[210:213], v[2:5]
	s_setprio 0
	s_barrier
	s_add_i32 s52, s52, 2
	s_add_u32 s18, s18, 0x100
	s_addc_u32 s19, s19, 0
	s_add_u32 s43, s43, 0x100
	s_addc_u32 s45, s45, 0
	s_cmp_gt_u32 s52, 13

; template <class Epi, class Sched, bool ALIGN_EPI = false, bool SP2 = false>
; __device__ __forceinline__ void gemm_phase(PG8_LAS unsigned char* lds, const Gemm g, const Sched& S, const Epi& E) {
;     ...
;         const bool has_next = S.next(ui + 1, nxt);
;         const char* nA = has_next ? (const char*)g.A + (size_t)nxt.pm * tstep : cA; const char* nB = has_next ? (const char*)g.Bt + (size_t)nxt.pn * tstep : cB;
;     ...
; #pragma unroll
;         for (int a = 0; a < 2; ++a)
; #pragma unroll
;             for (int b = 0; b < 2; ++b)
; #pragma unroll
;                 for (int m = 0; m < 4; ++m)
; #pragma unroll
;                     for (int n = 0; n < 2; ++n) acc[a][b][m][n] = (f32x4){0.f, 0.f, 0.f, 0.f};
.LBB0_452:
	s_ashr_i32 s51, s50, 31
	s_lshl_b64 s[30:31], s[50:51], 19
	s_add_u32 s56, s98, s30
	s_addc_u32 s57, s99, s31
	s_and_b64 s[30:31], s[54:55], exec
	s_cselect_b32 s30, s57, s19
	s_cselect_b32 s31, s56, s18
	s_ashr_i32 s49, s48, 31
	s_lshl_b64 s[34:35], s[48:49], 19
	s_add_u32 s58, s68, s34
	s_addc_u32 s59, s69, s35
	s_and_b64 s[34:35], s[54:55], exec
	s_cselect_b32 s34, s59, s65
	s_cselect_b32 s35, s58, s64
	s_add_u32 s18, s18, 0x40080
	s_addc_u32 s19, s19, 0
	s_add_u32 s49, s64, 0x100

; template <class Epi, class Sched, bool ALIGN_EPI = false, bool SP2 = false>
; __device__ __forceinline__ void gemm_phase(PG8_LAS unsigned char* lds, const Gemm g, const Sched& S, const Epi& E) {
;     ...
;         for (int t = 0; t < nt; t += 2) {
;     ...
; #pragma unroll
;         for (int a = 0; a < 2; ++a)
; #pragma unroll
;             for (int b = 0; b < 2; ++b)
; #pragma unroll
;                 for (int m = 0; m < 4; ++m)
; #pragma unroll
;                     for (int n = 0; n < 2; ++n) acc[a][b][m][n] = (f32x4){0.f, 0.f, 0.f, 0.f};
	s_addc_u32 s51, s65, 0
	s_mov_b32 s52, -2


; template <class Epi, class Sched, bool ALIGN_EPI = false, bool SP2 = false>
; __device__ __forceinline__ void gemm_phase(PG8_LAS unsigned char* lds, const Gemm g, const Sched& S, const Epi& E) {
;     ...
; #pragma unroll
;         for (int a = 0; a < 2; ++a)
; #pragma unroll
;             for (int b = 0; b < 2; ++b)
; #pragma unroll
;                 for (int m = 0; m < 4; ++m)
; #pragma unroll
;                     for (int n = 0; n < 2; ++n) acc[a][b][m][n] = (f32x4){0.f, 0.f, 0.f, 0.f};
	s_waitcnt vmcnt(0)


; #define PG8_STAGE(bufoff, gbase, voff) do { _Pragma("unroll") for (int _i = 0; _i < 2; ++_i) \
;         __builtin_amdgcn_global_load_lds((const unsigned*)((const char*)(gbase) + (voff)[_i]), (PG8_LAS unsigned*)(lds + (bufoff) + ldsw + _i * 8192), 16, 0, 0); } while (0)
; #define PG8_LDA(dst, b, h) do { _Pragma("unroll") for (int m = 0; m < 4; ++m) _Pragma("unroll") for (int k = 0; k < 2; ++k) dst[m][k] = *(const PG8_LAS bf16x8*)(lds + PG8_SA(b, h) + aoff + m * 2048 + k * 1024); } while (0)
; #define PG8_LDB(dst, b, h) do { _Pragma("unroll") for (int n = 0; n < 2; ++n) _Pragma("unroll") for (int k = 0; k < 2; ++k) dst[n][k] = *(const PG8_LAS bf16x8*)(lds + PG8_SB(b, h) + boff + n * 2048 + k * 1024); } while (0)
; #define PG8_MMA(ai, bj, At, Bt) do { __builtin_amdgcn_s_setprio(1); _Pragma("unroll") for (int m = 0; m < 4; ++m) _Pragma("unroll") for (int n = 0; n < 2; ++n) _Pragma("unroll") for (int k = 0; k < 2; ++k) \
;         acc[ai][bj][m][n] = __builtin_amdgcn_mfma_f32_16x16x32_bf16(Bt[n][k], At[m][k], acc[ai][bj][m][n], 0, 0, 0); __builtin_amdgcn_s_setprio(0); } while (0)
; #define PG8_WAIT_V(n) asm volatile("s_waitcnt vmcnt(" #n ")" ::: "memory")
; #define PG8_WAIT_L(n) asm volatile("s_waitcnt lgkmcnt(" #n ")" ::: "memory")
; #define PG8_BAR __builtin_amdgcn_s_barrier()
; #define PG8_SCHED __builtin_amdgcn_sched_barrier(0)
; template <class Epi, class Sched, bool ALIGN_EPI = false, bool SP2 = false>
; __device__ __forceinline__ void gemm_phase(PG8_LAS unsigned char* lds, const Gemm g, const Sched& S, const Epi& E) {
;     ...
;             const bool last = (t == nt - 2);
;             const char* a1 = cA + (size_t)(t + 1) * kstep;
;             const char* a2 = last ? nA : cA + (size_t)(t + 2) * kstep; const char* b2 = last ? nB : cB + (size_t)(t + 2) * kstep;
;             const char* a3 = a2 + kstep; const char* b3 = b2 + kstep;
;             if (last && has_next) S.a_ready(nxt);
;             if constexpr (SP2) {
;             PG8_LDB(B0, 0, 0); PG8_LDB(B1, 0, 1); PG8_SCHED; PG8_LDA(At, 0, 0); PG8_STAGE(PG8_SA(1, 1), a1 + hstep, voffA);
;             PG8_WAIT_V(8); PG8_WAIT_L(0); PG8_BAR; PG8_MMA(0, 0, At, B0); PG8_MMA(0, 1, At, B1); PG8_BAR; PG8_SCHED;
;             PG8_LDA(At, 0, 1); PG8_STAGE(PG8_SB(0, 0), b2, voffB); PG8_STAGE(PG8_SB(0, 1), b2 + hstep, voffB); PG8_STAGE(PG8_SA(0, 0), a2, voffA);
	s_add_u32 s53, s18, 0xfffc0080
	s_addc_u32 s64, s19, -1
	s_add_i32 s70, 0, 0x10000
	s_cmp_eq_u32 s52, 12
	s_cselect_b32 s67, s30, s64
	s_cselect_b32 s66, s31, s53
	s_cselect_b32 s65, s34, s51
	s_cselect_b32 s64, s35, s49
	s_add_i32 s53, 0, 0x14000
	v_add_u32_e32 v142, s70, v223
	v_add_u32_e32 v158, s53, v223
	ds_read_b128 v[130:133], v142
	ds_read_b128 v[134:137], v142 offset:1024
	ds_read_b128 v[138:141], v142 offset:2048
	ds_read_b128 v[142:145], v142 offset:3072
	ds_read_b128 v[146:149], v158
	ds_read_b128 v[150:153], v158 offset:1024
	ds_read_b128 v[154:157], v158 offset:2048
	ds_read_b128 v[158:161], v158 offset:3072
	v_lshl_add_u64 v[208:209], s[18:19], 0, v[200:201]
	s_add_i32 m0, s25, 0xc000
	ds_read_b128 v[162:165], v225
	ds_read_b128 v[166:169], v225 offset:1024
	ds_read_b128 v[170:173], v225 offset:2048
	ds_read_b128 v[174:177], v225 offset:3072
	ds_read_b128 v[178:181], v225 offset:4096
	ds_read_b128 v[182:185], v225 offset:5120
	ds_read_b128 v[186:189], v225 offset:6144
	ds_read_b128 v[204:207], v225 offset:7168
	global_load_lds_dwordx4 v[208:209], off
	v_lshl_add_u64 v[208:209], s[18:19], 0, v[202:203]
	s_add_i32 m0, s25, 0xe000
	s_nop 0
	global_load_lds_dwordx4 v[208:209], off
	s_waitcnt vmcnt(8)
	s_waitcnt lgkmcnt(0)
	s_barrier
	s_setprio 1
	s_waitcnt lgkmcnt(0)
	v_mfma_f32_16x16x32_bf16 v[126:129], v[130:133], v[162:165], 0
	v_mfma_f32_16x16x32_bf16 v[122:125], v[138:141], v[162:165], 0
	v_mfma_f32_16x16x32_bf16 v[110:113], v[130:133], v[170:173], 0
	v_mfma_f32_16x16x32_bf16 v[106:109], v[138:141], v[170:173], 0
	v_mfma_f32_16x16x32_bf16 v[98:101], v[130:133], v[178:181], 0
	v_mfma_f32_16x16x32_bf16 v[90:93], v[138:141], v[178:181], 0
	v_mfma_f32_16x16x32_bf16 v[82:85], v[130:133], v[186:189], 0
	v_mfma_f32_16x16x32_bf16 v[74:77], v[138:141], v[186:189], 0
	v_mfma_f32_16x16x32_bf16 v[126:129], v[134:137], v[166:169], v[126:129]
	v_mfma_f32_16x16x32_bf16 v[122:125], v[142:145], v[166:169], v[122:125]
	v_mfma_f32_16x16x32_bf16 v[110:113], v[134:137], v[174:177], v[110:113]
	v_mfma_f32_16x16x32_bf16 v[106:109], v[142:145], v[174:177], v[106:109]
	v_mfma_f32_16x16x32_bf16 v[98:101], v[134:137], v[182:185], v[98:101]
	v_mfma_f32_16x16x32_bf16 v[90:93], v[142:145], v[182:185], v[90:93]
	v_mfma_f32_16x16x32_bf16 v[82:85], v[134:137], v[204:207], v[82:85]
	v_mfma_f32_16x16x32_bf16 v[74:77], v[142:145], v[204:207], v[74:77]
	s_setprio 0
	s_setprio 1
	v_mfma_f32_16x16x32_bf16 v[118:121], v[146:149], v[162:165], 0
	v_mfma_f32_16x16x32_bf16 v[114:117], v[154:157], v[162:165], 0
	v_mfma_f32_16x16x32_bf16 v[102:105], v[146:149], v[170:173], 0
	v_mfma_f32_16x16x32_bf16 v[94:97], v[154:157], v[170:173], 0
	v_mfma_f32_16x16x32_bf16 v[86:89], v[146:149], v[178:181], 0
	v_mfma_f32_16x16x32_bf16 v[78:81], v[154:157], v[178:181], 0
	v_mfma_f32_16x16x32_bf16 v[70:73], v[146:149], v[186:189], 0
	v_mfma_f32_16x16x32_bf16 v[66:69], v[154:157], v[186:189], 0
	v_mfma_f32_16x16x32_bf16 v[118:121], v[150:153], v[166:169], v[118:121]
	v_mfma_f32_16x16x32_bf16 v[114:117], v[158:161], v[166:169], v[114:117]
	v_mfma_f32_16x16x32_bf16 v[102:105], v[150:153], v[174:177], v[102:105]
	v_mfma_f32_16x16x32_bf16 v[94:97], v[158:161], v[174:177], v[94:97]
	v_mfma_f32_16x16x32_bf16 v[86:89], v[150:153], v[182:185], v[86:89]
	v_mfma_f32_16x16x32_bf16 v[78:81], v[158:161], v[182:185], v[78:81]
	v_mfma_f32_16x16x32_bf16 v[70:73], v[150:153], v[204:207], v[70:73]
	v_mfma_f32_16x16x32_bf16 v[66:69], v[158:161], v[204:207], v[66:69]
	s_setprio 0
	s_barrier
	s_add_i32 s70, s70, s24
	v_lshl_add_u64 v[208:209], s[64:65], 0, v[0:1]
	s_mov_b32 m0, s70
	ds_read_b128 v[162:165], v225 offset:16384
	ds_read_b128 v[166:169], v225 offset:17408
	ds_read_b128 v[170:173], v225 offset:18432
	ds_read_b128 v[174:177], v225 offset:19456
	ds_read_b128 v[178:181], v225 offset:20480
	ds_read_b128 v[182:185], v225 offset:21504
	ds_read_b128 v[186:189], v225 offset:22528
	ds_read_b128 v[204:207], v225 offset:23552
	global_load_lds_dwordx4 v[208:209], off
	s_add_i32 m0, s70, 0x2000
	s_add_u32 s70, s64, 0x40000
	v_lshl_add_u64 v[210:211], s[64:65], 0, v[198:199]
	s_addc_u32 s71, s65, 0
	s_add_i32 s53, s53, s24
	global_load_lds_dwordx4 v[210:211], off
	v_lshl_add_u64 v[212:213], s[70:71], 0, v[0:1]
	s_mov_b32 m0, s53
	v_lshl_add_u64 v[214:215], s[66:67], 0, v[196:197]
	global_load_lds_dwordx4 v[212:213], off
	v_lshl_add_u64 v[212:213], s[70:71], 0, v[198:199]
	s_add_i32 m0, s53, 0x2000
	s_nop 0
	global_load_lds_dwordx4 v[212:213], off
	v_lshl_add_u64 v[212:213], s[66:67], 0, v[194:195]
	s_mov_b32 m0, s25
	s_nop 0
	global_load_lds_dwordx4 v[212:213], off
	s_mov_b32 m0, s26
	s_nop 0
	global_load_lds_dwordx4 v[214:215], off
	s_waitcnt vmcnt(8)
	s_waitcnt lgkmcnt(0)
	s_barrier
; #define PG8_STAGE(bufoff, gbase, voff) do { _Pragma("unroll") for (int _i = 0; _i < 2; ++_i) \
;         __builtin_amdgcn_global_load_lds((const unsigned*)((const char*)(gbase) + (voff)[_i]), (PG8_LAS unsigned*)(lds + (bufoff) + ldsw + _i * 8192), 16, 0, 0); } while (0)
; #define PG8_LDA(dst, b, h) do { _Pragma("unroll") for (int m = 0; m < 4; ++m) _Pragma("unroll") for (int k = 0; k < 2; ++k) dst[m][k] = *(const PG8_LAS bf16x8*)(lds + PG8_SA(b, h) + aoff + m * 2048 + k * 1024); } while (0)
; #define PG8_LDB(dst, b, h) do { _Pragma("unroll") for (int n = 0; n < 2; ++n) _Pragma("unroll") for (int k = 0; k < 2; ++k) dst[n][k] = *(const PG8_LAS bf16x8*)(lds + PG8_SB(b, h) + boff + n * 2048 + k * 1024); } while (0)
; #define PG8_MMA(ai, bj, At, Bt) do { __builtin_amdgcn_s_setprio(1); _Pragma("unroll") for (int m = 0; m < 4; ++m) _Pragma("unroll") for (int n = 0; n < 2; ++n) _Pragma("unroll") for (int k = 0; k < 2; ++k) \
;         acc[ai][bj][m][n] = __builtin_amdgcn_mfma_f32_16x16x32_bf16(Bt[n][k], At[m][k], acc[ai][bj][m][n], 0, 0, 0); __builtin_amdgcn_s_setprio(0); } while (0)
; #define PG8_WAIT_V(n) asm volatile("s_waitcnt vmcnt(" #n ")" ::: "memory")
; #define PG8_WAIT_L(n) asm volatile("s_waitcnt lgkmcnt(" #n ")" ::: "memory")
; #define PG8_BAR __builtin_amdgcn_s_barrier()
; #define PG8_SCHED __builtin_amdgcn_sched_barrier(0)
; template <class Epi, class Sched, bool ALIGN_EPI = false, bool SP2 = false>
; __device__ __forceinline__ void gemm_phase(PG8_LAS unsigned char* lds, const Gemm g, const Sched& S, const Epi& E) {
;     ...
;             PG8_WAIT_V(8); PG8_WAIT_L(0); PG8_BAR; PG8_MMA(1, 0, At, B0); PG8_MMA(1, 1, At, B1); PG8_BAR; PG8_SCHED;
;             PG8_LDB(B0, 1, 0); PG8_LDB(B1, 1, 1); PG8_SCHED; PG8_LDA(At, 1, 0); PG8_STAGE(PG8_SA(0, 1), a2 + hstep, voffA);
;             PG8_WAIT_V(8); PG8_WAIT_L(0); PG8_BAR; PG8_MMA(0, 0, At, B0); PG8_MMA(0, 1, At, B1); PG8_BAR; PG8_SCHED;
	s_setprio 1
	s_waitcnt lgkmcnt(0)
	v_mfma_f32_16x16x32_bf16 v[62:65], v[130:133], v[162:165], 0
	v_mfma_f32_16x16x32_bf16 v[58:61], v[138:141], v[162:165], 0
	v_mfma_f32_16x16x32_bf16 v[50:53], v[130:133], v[170:173], 0
	v_mfma_f32_16x16x32_bf16 v[42:45], v[138:141], v[170:173], 0
	v_mfma_f32_16x16x32_bf16 v[34:37], v[130:133], v[178:181], 0
	v_mfma_f32_16x16x32_bf16 v[26:29], v[138:141], v[178:181], 0
	v_mfma_f32_16x16x32_bf16 v[18:21], v[130:133], v[186:189], 0
	v_mfma_f32_16x16x32_bf16 v[10:13], v[138:141], v[186:189], 0
	v_mfma_f32_16x16x32_bf16 v[62:65], v[134:137], v[166:169], v[62:65]
	v_mfma_f32_16x16x32_bf16 v[58:61], v[142:145], v[166:169], v[58:61]
	v_mfma_f32_16x16x32_bf16 v[50:53], v[134:137], v[174:177], v[50:53]
	v_mfma_f32_16x16x32_bf16 v[42:45], v[142:145], v[174:177], v[42:45]
	v_mfma_f32_16x16x32_bf16 v[34:37], v[134:137], v[182:185], v[34:37]
	v_mfma_f32_16x16x32_bf16 v[26:29], v[142:145], v[182:185], v[26:29]
	v_mfma_f32_16x16x32_bf16 v[18:21], v[134:137], v[204:207], v[18:21]
	v_mfma_f32_16x16x32_bf16 v[10:13], v[142:145], v[204:207], v[10:13]
	s_setprio 0
	s_setprio 1
	v_mfma_f32_16x16x32_bf16 v[54:57], v[146:149], v[162:165], 0
	v_mfma_f32_16x16x32_bf16 v[46:49], v[154:157], v[162:165], 0
	v_mfma_f32_16x16x32_bf16 v[38:41], v[146:149], v[170:173], 0
	v_mfma_f32_16x16x32_bf16 v[30:33], v[154:157], v[170:173], 0
	v_mfma_f32_16x16x32_bf16 v[22:25], v[146:149], v[178:181], 0
	v_mfma_f32_16x16x32_bf16 v[14:17], v[154:157], v[178:181], 0
	v_mfma_f32_16x16x32_bf16 v[6:9], v[146:149], v[186:189], 0
	v_mfma_f32_16x16x32_bf16 v[2:5], v[154:157], v[186:189], 0
	v_mfma_f32_16x16x32_bf16 v[54:57], v[150:153], v[166:169], v[54:57]
	v_mfma_f32_16x16x32_bf16 v[46:49], v[158:161], v[166:169], v[46:49]
	v_mfma_f32_16x16x32_bf16 v[38:41], v[150:153], v[174:177], v[38:41]
	v_mfma_f32_16x16x32_bf16 v[30:33], v[158:161], v[174:177], v[30:33]
	v_mfma_f32_16x16x32_bf16 v[22:25], v[150:153], v[182:185], v[22:25]
	v_mfma_f32_16x16x32_bf16 v[14:17], v[158:161], v[182:185], v[14:17]
	v_mfma_f32_16x16x32_bf16 v[6:9], v[150:153], v[204:207], v[6:9]
	v_mfma_f32_16x16x32_bf16 v[2:5], v[158:161], v[204:207], v[2:5]
	s_setprio 0
	s_barrier
	s_add_i32 s53, 0, 0x18000
	s_add_i32 s70, 0, 0x1c000
	v_add_u32_e32 v142, s53, v223
	v_add_u32_e32 v158, s70, v223
	ds_read_b128 v[130:133], v142
	ds_read_b128 v[134:137], v142 offset:1024
	ds_read_b128 v[138:141], v142 offset:2048
	ds_read_b128 v[142:145], v142 offset:3072
	ds_read_b128 v[146:149], v158
	ds_read_b128 v[150:153], v158 offset:1024
	ds_read_b128 v[154:157], v158 offset:2048
	ds_read_b128 v[158:161], v158 offset:3072
	s_add_u32 s66, s66, 0x40000
	s_addc_u32 s67, s67, 0
	s_mov_b32 m0, s27
	v_lshl_add_u64 v[216:217], s[66:67], 0, v[194:195]
	ds_read_b128 v[162:165], v225 offset:32768
	ds_read_b128 v[166:169], v225 offset:33792
	ds_read_b128 v[170:173], v225 offset:34816
	ds_read_b128 v[174:177], v225 offset:35840
	ds_read_b128 v[178:181], v225 offset:36864
	ds_read_b128 v[182:185], v225 offset:37888
	ds_read_b128 v[186:189], v225 offset:38912
	ds_read_b128 v[204:207], v225 offset:39936
	global_load_lds_dwordx4 v[216:217], off
	v_lshl_add_u64 v[216:217], s[66:67], 0, v[196:197]
	s_mov_b32 m0, s28
	s_nop 0
	global_load_lds_dwordx4 v[216:217], off
	s_waitcnt vmcnt(8)
	s_waitcnt lgkmcnt(0)
	s_barrier
	s_setprio 1
	s_waitcnt lgkmcnt(0)
	v_mfma_f32_16x16x32_bf16 v[126:129], v[130:133], v[162:165], v[126:129]
	v_mfma_f32_16x16x32_bf16 v[122:125], v[138:141], v[162:165], v[122:125]
	v_mfma_f32_16x16x32_bf16 v[110:113], v[130:133], v[170:173], v[110:113]
	v_mfma_f32_16x16x32_bf16 v[106:109], v[138:141], v[170:173], v[106:109]
	v_mfma_f32_16x16x32_bf16 v[98:101], v[130:133], v[178:181], v[98:101]
	v_mfma_f32_16x16x32_bf16 v[90:93], v[138:141], v[178:181], v[90:93]
	v_mfma_f32_16x16x32_bf16 v[82:85], v[130:133], v[186:189], v[82:85]
	v_mfma_f32_16x16x32_bf16 v[74:77], v[138:141], v[186:189], v[74:77]
	v_mfma_f32_16x16x32_bf16 v[126:129], v[134:137], v[166:169], v[126:129]
	v_mfma_f32_16x16x32_bf16 v[122:125], v[142:145], v[166:169], v[122:125]
	v_mfma_f32_16x16x32_bf16 v[110:113], v[134:137], v[174:177], v[110:113]
	v_mfma_f32_16x16x32_bf16 v[106:109], v[142:145], v[174:177], v[106:109]
	v_mfma_f32_16x16x32_bf16 v[98:101], v[134:137], v[182:185], v[98:101]
	v_mfma_f32_16x16x32_bf16 v[90:93], v[142:145], v[182:185], v[90:93]
	v_mfma_f32_16x16x32_bf16 v[82:85], v[134:137], v[204:207], v[82:85]
	v_mfma_f32_16x16x32_bf16 v[74:77], v[142:145], v[204:207], v[74:77]
	s_setprio 0
	s_setprio 1
	v_mfma_f32_16x16x32_bf16 v[118:121], v[146:149], v[162:165], v[118:121]
	v_mfma_f32_16x16x32_bf16 v[114:117], v[154:157], v[162:165], v[114:117]
	v_mfma_f32_16x16x32_bf16 v[102:105], v[146:149], v[170:173], v[102:105]
	v_mfma_f32_16x16x32_bf16 v[94:97], v[154:157], v[170:173], v[94:97]
	v_mfma_f32_16x16x32_bf16 v[86:89], v[146:149], v[178:181], v[86:89]
	v_mfma_f32_16x16x32_bf16 v[78:81], v[154:157], v[178:181], v[78:81]
	v_mfma_f32_16x16x32_bf16 v[70:73], v[146:149], v[186:189], v[70:73]
	v_mfma_f32_16x16x32_bf16 v[66:69], v[154:157], v[186:189], v[66:69]
	v_mfma_f32_16x16x32_bf16 v[118:121], v[150:153], v[166:169], v[118:121]
	v_mfma_f32_16x16x32_bf16 v[114:117], v[158:161], v[166:169], v[114:117]
	v_mfma_f32_16x16x32_bf16 v[102:105], v[150:153], v[174:177], v[102:105]
	v_mfma_f32_16x16x32_bf16 v[94:97], v[158:161], v[174:177], v[94:97]
	v_mfma_f32_16x16x32_bf16 v[86:89], v[150:153], v[182:185], v[86:89]
	v_mfma_f32_16x16x32_bf16 v[78:81], v[158:161], v[182:185], v[78:81]
	v_mfma_f32_16x16x32_bf16 v[70:73], v[150:153], v[204:207], v[70:73]
	v_mfma_f32_16x16x32_bf16 v[66:69], v[158:161], v[204:207], v[66:69]
	s_setprio 0
	s_barrier
; #define PG8_STAGE(bufoff, gbase, voff) do { _Pragma("unroll") for (int _i = 0; _i < 2; ++_i) \
;         __builtin_amdgcn_global_load_lds((const unsigned*)((const char*)(gbase) + (voff)[_i]), (PG8_LAS unsigned*)(lds + (bufoff) + ldsw + _i * 8192), 16, 0, 0); } while (0)
; #define PG8_LDA(dst, b, h) do { _Pragma("unroll") for (int m = 0; m < 4; ++m) _Pragma("unroll") for (int k = 0; k < 2; ++k) dst[m][k] = *(const PG8_LAS bf16x8*)(lds + PG8_SA(b, h) + aoff + m * 2048 + k * 1024); } while (0)
; #define PG8_MMA(ai, bj, At, Bt) do { __builtin_amdgcn_s_setprio(1); _Pragma("unroll") for (int m = 0; m < 4; ++m) _Pragma("unroll") for (int n = 0; n < 2; ++n) _Pragma("unroll") for (int k = 0; k < 2; ++k) \
;         acc[ai][bj][m][n] = __builtin_amdgcn_mfma_f32_16x16x32_bf16(Bt[n][k], At[m][k], acc[ai][bj][m][n], 0, 0, 0); __builtin_amdgcn_s_setprio(0); } while (0)
; #define PG8_WAIT_V(n) asm volatile("s_waitcnt vmcnt(" #n ")" ::: "memory")
; #define PG8_WAIT_L(n) asm volatile("s_waitcnt lgkmcnt(" #n ")" ::: "memory")
; #define PG8_BAR __builtin_amdgcn_s_barrier()
; #define PG8_SCHED __builtin_amdgcn_sched_barrier(0)
; template <class Epi, class Sched, bool ALIGN_EPI = false, bool SP2 = false>
; __device__ __forceinline__ void gemm_phase(PG8_LAS unsigned char* lds, const Gemm g, const Sched& S, const Epi& E) {
;     ...
;         for (int t = 0; t < nt; t += 2) {
;     ...
;             PG8_LDA(At, 1, 1); PG8_STAGE(PG8_SB(1, 0), b3, voffB); PG8_STAGE(PG8_SB(1, 1), b3 + hstep, voffB); PG8_STAGE(PG8_SA(1, 0), a3, voffA);
;             PG8_WAIT_V(8); PG8_WAIT_L(0); PG8_BAR; PG8_MMA(1, 0, At, B0); PG8_MMA(1, 1, At, B1); PG8_BAR; PG8_SCHED;
	s_add_i32 s53, s53, s24
	v_lshl_add_u64 v[208:209], v[208:209], 0, s[8:9]
	s_mov_b32 m0, s53
	ds_read_b128 v[162:165], v225 offset:49152
	ds_read_b128 v[166:169], v225 offset:50176
	ds_read_b128 v[170:173], v225 offset:51200
	ds_read_b128 v[174:177], v225 offset:52224
	ds_read_b128 v[178:181], v225 offset:53248
	ds_read_b128 v[182:185], v225 offset:54272
	ds_read_b128 v[186:189], v225 offset:55296
	ds_read_b128 v[204:207], v225 offset:56320
	global_load_lds_dwordx4 v[208:209], off
	s_add_i32 m0, s53, 0x2000
	s_add_u32 s64, s64, 0x40080
	v_lshl_add_u64 v[208:209], v[210:211], 0, s[8:9]
	s_addc_u32 s65, s65, 0
	s_add_i32 s53, s70, s24
	global_load_lds_dwordx4 v[208:209], off
	v_lshl_add_u64 v[208:209], s[64:65], 0, v[0:1]
	s_mov_b32 m0, s53
	s_nop 0
	global_load_lds_dwordx4 v[208:209], off
	v_lshl_add_u64 v[208:209], s[64:65], 0, v[198:199]
	s_add_i32 m0, s53, 0x2000
	s_nop 0
	global_load_lds_dwordx4 v[208:209], off
	v_lshl_add_u64 v[208:209], v[212:213], 0, s[8:9]
	s_mov_b32 m0, s29
	s_nop 0
	global_load_lds_dwordx4 v[208:209], off
	v_lshl_add_u64 v[208:209], v[214:215], 0, s[8:9]
	s_mov_b32 m0, s61
	s_nop 0
	global_load_lds_dwordx4 v[208:209], off
	s_waitcnt vmcnt(8)
	s_waitcnt lgkmcnt(0)
	s_barrier
	s_setprio 1
	s_waitcnt lgkmcnt(0)
	v_mfma_f32_16x16x32_bf16 v[62:65], v[130:133], v[162:165], v[62:65]
	v_mfma_f32_16x16x32_bf16 v[58:61], v[138:141], v[162:165], v[58:61]
	v_mfma_f32_16x16x32_bf16 v[50:53], v[130:133], v[170:173], v[50:53]
	v_mfma_f32_16x16x32_bf16 v[42:45], v[138:141], v[170:173], v[42:45]
	v_mfma_f32_16x16x32_bf16 v[34:37], v[130:133], v[178:181], v[34:37]
	v_mfma_f32_16x16x32_bf16 v[26:29], v[138:141], v[178:181], v[26:29]
	v_mfma_f32_16x16x32_bf16 v[18:21], v[130:133], v[186:189], v[18:21]
	v_mfma_f32_16x16x32_bf16 v[10:13], v[138:141], v[186:189], v[10:13]
	v_mfma_f32_16x16x32_bf16 v[62:65], v[134:137], v[166:169], v[62:65]
	v_mfma_f32_16x16x32_bf16 v[58:61], v[142:145], v[166:169], v[58:61]
	v_mfma_f32_16x16x32_bf16 v[50:53], v[134:137], v[174:177], v[50:53]
	v_mfma_f32_16x16x32_bf16 v[42:45], v[142:145], v[174:177], v[42:45]
	v_mfma_f32_16x16x32_bf16 v[34:37], v[134:137], v[182:185], v[34:37]
	v_mfma_f32_16x16x32_bf16 v[26:29], v[142:145], v[182:185], v[26:29]
	v_mfma_f32_16x16x32_bf16 v[18:21], v[134:137], v[204:207], v[18:21]
	v_mfma_f32_16x16x32_bf16 v[10:13], v[142:145], v[204:207], v[10:13]
	s_setprio 0
	s_setprio 1
	v_mfma_f32_16x16x32_bf16 v[54:57], v[146:149], v[162:165], v[54:57]
	v_mfma_f32_16x16x32_bf16 v[46:49], v[154:157], v[162:165], v[46:49]
	v_mfma_f32_16x16x32_bf16 v[38:41], v[146:149], v[170:173], v[38:41]
	v_mfma_f32_16x16x32_bf16 v[30:33], v[154:157], v[170:173], v[30:33]
	v_mfma_f32_16x16x32_bf16 v[22:25], v[146:149], v[178:181], v[22:25]
	v_mfma_f32_16x16x32_bf16 v[14:17], v[154:157], v[178:181], v[14:17]
	v_mfma_f32_16x16x32_bf16 v[6:9], v[146:149], v[186:189], v[6:9]
	v_mfma_f32_16x16x32_bf16 v[2:5], v[154:157], v[186:189], v[2:5]
	v_mfma_f32_16x16x32_bf16 v[54:57], v[150:153], v[166:169], v[54:57]
	v_mfma_f32_16x16x32_bf16 v[46:49], v[158:161], v[166:169], v[46:49]
	v_mfma_f32_16x16x32_bf16 v[38:41], v[150:153], v[174:177], v[38:41]
	v_mfma_f32_16x16x32_bf16 v[30:33], v[158:161], v[174:177], v[30:33]
	v_mfma_f32_16x16x32_bf16 v[22:25], v[150:153], v[182:185], v[22:25]
	v_mfma_f32_16x16x32_bf16 v[14:17], v[158:161], v[182:185], v[14:17]
	v_mfma_f32_16x16x32_bf16 v[6:9], v[150:153], v[204:207], v[6:9]
	v_mfma_f32_16x16x32_bf16 v[2:5], v[158:161], v[204:207], v[2:5]
	s_setprio 0
	s_barrier
	s_add_i32 s52, s52, 2
	s_add_u32 s18, s18, 0x100
	s_addc_u32 s19, s19, 0
	s_add_u32 s49, s49, 0x100
	s_addc_u32 s51, s51, 0
	s_cmp_gt_u32 s52, 13

; template <class Epi, class Sched, bool ALIGN_EPI = false, bool SP2 = false>
; __device__ __forceinline__ void gemm_phase(PG8_LAS unsigned char* lds, const Gemm g, const Sched& S, const Epi& E) {
;     ...
;         const bool has_next = S.next(ui + 1, nxt);
;         const char* nA = has_next ? (const char*)g.A + (size_t)nxt.pm * tstep : cA; const char* nB = has_next ? (const char*)g.Bt + (size_t)nxt.pn * tstep : cB;
;     ...
; #pragma unroll
;         for (int a = 0; a < 2; ++a)
; #pragma unroll
;             for (int b = 0; b < 2; ++b)
; #pragma unroll
;                 for (int m = 0; m < 4; ++m)
; #pragma unroll
;                     for (int n = 0; n < 2; ++n) acc[a][b][m][n] = (f32x4){0.f, 0.f, 0.f, 0.f};
.LBB0_486:
	s_ashr_i32 s47, s46, 31
	s_lshl_b64 s[30:31], s[46:47], 19
	s_add_u32 s50, s98, s30
	s_addc_u32 s51, s99, s31
	s_and_b64 s[30:31], s[48:49], exec
	s_cselect_b32 s30, s51, s19
	s_cselect_b32 s31, s50, s18
	s_ashr_i32 s45, s44, 31
	s_lshl_b64 s[34:35], s[44:45], 19
	s_add_u32 s54, s68, s34
	s_addc_u32 s55, s69, s35
	s_and_b64 s[34:35], s[48:49], exec
	s_cselect_b32 s34, s55, s61
	s_cselect_b32 s35, s54, s60
	s_add_u32 s18, s18, 0x40080
	s_addc_u32 s19, s19, 0
	s_add_u32 s45, s60, 0x100

; template <class Epi, class Sched, bool ALIGN_EPI = false, bool SP2 = false>
; __device__ __forceinline__ void gemm_phase(PG8_LAS unsigned char* lds, const Gemm g, const Sched& S, const Epi& E) {
;     ...
;         for (int t = 0; t < nt; t += 2) {
;     ...
; #pragma unroll
;         for (int a = 0; a < 2; ++a)
; #pragma unroll
;             for (int b = 0; b < 2; ++b)
; #pragma unroll
;                 for (int m = 0; m < 4; ++m)
; #pragma unroll
;                     for (int n = 0; n < 2; ++n) acc[a][b][m][n] = (f32x4){0.f, 0.f, 0.f, 0.f};
	s_addc_u32 s47, s61, 0
	s_mov_b32 s52, -2


; template <class Epi, class Sched, bool ALIGN_EPI = false, bool SP2 = false>
; __device__ __forceinline__ void gemm_phase(PG8_LAS unsigned char* lds, const Gemm g, const Sched& S, const Epi& E) {
;     ...
; #pragma unroll
;         for (int a = 0; a < 2; ++a)
; #pragma unroll
;             for (int b = 0; b < 2; ++b)
; #pragma unroll
;                 for (int m = 0; m < 4; ++m)
; #pragma unroll
;                     for (int n = 0; n < 2; ++n) acc[a][b][m][n] = (f32x4){0.f, 0.f, 0.f, 0.f};
	s_waitcnt lgkmcnt(0)


; template <class Epi, class Sched, bool ALIGN_EPI = false, bool SP2 = false>
; __device__ __forceinline__ void gemm_phase(PG8_LAS unsigned char* lds, const Gemm g, const Sched& S, const Epi& E) {
;     ...
; #pragma unroll
;         for (int a = 0; a < 2; ++a)
; #pragma unroll
;             for (int b = 0; b < 2; ++b)
; #pragma unroll
;                 for (int m = 0; m < 4; ++m)
; #pragma unroll
;                     for (int n = 0; n < 2; ++n) acc[a][b][m][n] = (f32x4){0.f, 0.f, 0.f, 0.f};
	s_waitcnt vmcnt(0)


; #define PG8_STAGE(bufoff, gbase, voff) do { _Pragma("unroll") for (int _i = 0; _i < 2; ++_i) \
;         __builtin_amdgcn_global_load_lds((const unsigned*)((const char*)(gbase) + (voff)[_i]), (PG8_LAS unsigned*)(lds + (bufoff) + ldsw + _i * 8192), 16, 0, 0); } while (0)
; #define PG8_LDA(dst, b, h) do { _Pragma("unroll") for (int m = 0; m < 4; ++m) _Pragma("unroll") for (int k = 0; k < 2; ++k) dst[m][k] = *(const PG8_LAS bf16x8*)(lds + PG8_SA(b, h) + aoff + m * 2048 + k * 1024); } while (0)
; #define PG8_LDB(dst, b, h) do { _Pragma("unroll") for (int n = 0; n < 2; ++n) _Pragma("unroll") for (int k = 0; k < 2; ++k) dst[n][k] = *(const PG8_LAS bf16x8*)(lds + PG8_SB(b, h) + boff + n * 2048 + k * 1024); } while (0)
; #define PG8_MMA(ai, bj, At, Bt) do { __builtin_amdgcn_s_setprio(1); _Pragma("unroll") for (int m = 0; m < 4; ++m) _Pragma("unroll") for (int n = 0; n < 2; ++n) _Pragma("unroll") for (int k = 0; k < 2; ++k) \
;         acc[ai][bj][m][n] = __builtin_amdgcn_mfma_f32_16x16x32_bf16(Bt[n][k], At[m][k], acc[ai][bj][m][n], 0, 0, 0); __builtin_amdgcn_s_setprio(0); } while (0)
; #define PG8_WAIT_V(n) asm volatile("s_waitcnt vmcnt(" #n ")" ::: "memory")
; #define PG8_WAIT_L(n) asm volatile("s_waitcnt lgkmcnt(" #n ")" ::: "memory")
; #define PG8_BAR __builtin_amdgcn_s_barrier()
; #define PG8_SCHED __builtin_amdgcn_sched_barrier(0)
; template <class Epi, class Sched, bool ALIGN_EPI = false, bool SP2 = false>
; __device__ __forceinline__ void gemm_phase(PG8_LAS unsigned char* lds, const Gemm g, const Sched& S, const Epi& E) {
;     ...
;             const bool last = (t == nt - 2);
;             const char* a1 = cA + (size_t)(t + 1) * kstep;
;             const char* a2 = last ? nA : cA + (size_t)(t + 2) * kstep; const char* b2 = last ? nB : cB + (size_t)(t + 2) * kstep;
;             const char* a3 = a2 + kstep; const char* b3 = b2 + kstep;
;             if (last && has_next) S.a_ready(nxt);
;             if constexpr (SP2) {
;             PG8_LDB(B0, 0, 0); PG8_LDB(B1, 0, 1); PG8_SCHED; PG8_LDA(At, 0, 0); PG8_STAGE(PG8_SA(1, 1), a1 + hstep, voffA);
;             PG8_WAIT_V(8); PG8_WAIT_L(0); PG8_BAR; PG8_MMA(0, 0, At, B0); PG8_MMA(0, 1, At, B1); PG8_BAR; PG8_SCHED;
;             PG8_LDA(At, 0, 1); PG8_STAGE(PG8_SB(0, 0), b2, voffB); PG8_STAGE(PG8_SB(0, 1), b2 + hstep, voffB); PG8_STAGE(PG8_SA(0, 0), a2, voffA);
	s_add_u32 s53, s18, 0xfffc0080
	s_addc_u32 s60, s19, -1
	s_add_i32 s64, 0, 0x10000
	s_cmp_eq_u32 s52, 12
	s_cselect_b32 s63, s30, s60
	s_cselect_b32 s62, s31, s53
	s_cselect_b32 s61, s34, s47
	s_cselect_b32 s60, s35, s45
	s_add_i32 s53, 0, 0x14000
	v_add_u32_e32 v134, s64, v239
	v_add_u32_e32 v158, s53, v239
	ds_read_b128 v[122:125], v134
	ds_read_b128 v[126:129], v134 offset:1024
	ds_read_b128 v[130:133], v134 offset:2048
	ds_read_b128 v[134:137], v134 offset:3072
	ds_read_b128 v[138:141], v158
	ds_read_b128 v[142:145], v158 offset:1024
	ds_read_b128 v[146:149], v158 offset:2048
	ds_read_b128 v[158:161], v158 offset:3072
	v_lshl_add_u64 v[212:213], s[18:19], 0, v[204:205]
	s_add_i32 m0, s25, 0xc000
	ds_read_b128 v[162:165], v241
	ds_read_b128 v[166:169], v241 offset:1024
	ds_read_b128 v[170:173], v241 offset:2048
	ds_read_b128 v[174:177], v241 offset:3072
	ds_read_b128 v[178:181], v241 offset:4096
	ds_read_b128 v[182:185], v241 offset:5120
	ds_read_b128 v[186:189], v241 offset:6144
	ds_read_b128 v[208:211], v241 offset:7168
	global_load_lds_dwordx4 v[212:213], off
	v_lshl_add_u64 v[212:213], s[18:19], 0, v[206:207]
	s_add_i32 m0, s25, 0xe000
	s_nop 0
	global_load_lds_dwordx4 v[212:213], off
	s_waitcnt vmcnt(8)
	s_waitcnt lgkmcnt(0)
	s_barrier
	s_setprio 1
	s_waitcnt lgkmcnt(0)
	v_mfma_f32_16x16x32_bf16 v[154:157], v[122:125], v[162:165], 0
	v_mfma_f32_16x16x32_bf16 v[150:153], v[130:133], v[162:165], 0
	v_mfma_f32_16x16x32_bf16 v[110:113], v[122:125], v[170:173], 0
	v_mfma_f32_16x16x32_bf16 v[106:109], v[130:133], v[170:173], 0
	v_mfma_f32_16x16x32_bf16 v[94:97], v[122:125], v[178:181], 0
	v_mfma_f32_16x16x32_bf16 v[90:93], v[130:133], v[178:181], 0
	v_mfma_f32_16x16x32_bf16 v[78:81], v[122:125], v[186:189], 0
	v_mfma_f32_16x16x32_bf16 v[74:77], v[130:133], v[186:189], 0
	v_mfma_f32_16x16x32_bf16 v[154:157], v[126:129], v[166:169], v[154:157]
	v_mfma_f32_16x16x32_bf16 v[150:153], v[134:137], v[166:169], v[150:153]
	v_mfma_f32_16x16x32_bf16 v[110:113], v[126:129], v[174:177], v[110:113]
	v_mfma_f32_16x16x32_bf16 v[106:109], v[134:137], v[174:177], v[106:109]
	v_mfma_f32_16x16x32_bf16 v[94:97], v[126:129], v[182:185], v[94:97]
	v_mfma_f32_16x16x32_bf16 v[90:93], v[134:137], v[182:185], v[90:93]
	v_mfma_f32_16x16x32_bf16 v[78:81], v[126:129], v[208:211], v[78:81]
	v_mfma_f32_16x16x32_bf16 v[74:77], v[134:137], v[208:211], v[74:77]
	s_setprio 0
	s_setprio 1
	v_mfma_f32_16x16x32_bf16 v[118:121], v[138:141], v[162:165], 0
	v_mfma_f32_16x16x32_bf16 v[114:117], v[146:149], v[162:165], 0
	v_mfma_f32_16x16x32_bf16 v[102:105], v[138:141], v[170:173], 0
	v_mfma_f32_16x16x32_bf16 v[98:101], v[146:149], v[170:173], 0
	v_mfma_f32_16x16x32_bf16 v[86:89], v[138:141], v[178:181], 0
	v_mfma_f32_16x16x32_bf16 v[82:85], v[146:149], v[178:181], 0
	v_mfma_f32_16x16x32_bf16 v[70:73], v[138:141], v[186:189], 0
	v_mfma_f32_16x16x32_bf16 v[66:69], v[146:149], v[186:189], 0
	v_mfma_f32_16x16x32_bf16 v[118:121], v[142:145], v[166:169], v[118:121]
	v_mfma_f32_16x16x32_bf16 v[114:117], v[158:161], v[166:169], v[114:117]
	v_mfma_f32_16x16x32_bf16 v[102:105], v[142:145], v[174:177], v[102:105]
	v_mfma_f32_16x16x32_bf16 v[98:101], v[158:161], v[174:177], v[98:101]
	v_mfma_f32_16x16x32_bf16 v[86:89], v[142:145], v[182:185], v[86:89]
	v_mfma_f32_16x16x32_bf16 v[82:85], v[158:161], v[182:185], v[82:85]
	v_mfma_f32_16x16x32_bf16 v[70:73], v[142:145], v[208:211], v[70:73]
	v_mfma_f32_16x16x32_bf16 v[66:69], v[158:161], v[208:211], v[66:69]
	s_setprio 0
	s_barrier
	s_add_i32 s64, s64, s24
	v_lshl_add_u64 v[212:213], s[60:61], 0, v[0:1]
	s_mov_b32 m0, s64
	ds_read_b128 v[162:165], v241 offset:16384
	ds_read_b128 v[166:169], v241 offset:17408
	ds_read_b128 v[170:173], v241 offset:18432
	ds_read_b128 v[174:177], v241 offset:19456
	ds_read_b128 v[178:181], v241 offset:20480
	ds_read_b128 v[182:185], v241 offset:21504
	ds_read_b128 v[186:189], v241 offset:22528
	ds_read_b128 v[208:211], v241 offset:23552
	global_load_lds_dwordx4 v[212:213], off
	s_add_i32 m0, s64, 0x2000
	s_add_u32 s64, s60, 0x40000
	v_lshl_add_u64 v[214:215], s[60:61], 0, v[198:199]
	s_addc_u32 s65, s61, 0
	s_add_i32 s53, s53, s24
	global_load_lds_dwordx4 v[214:215], off
	v_lshl_add_u64 v[216:217], s[64:65], 0, v[0:1]
	s_mov_b32 m0, s53
	v_lshl_add_u64 v[218:219], s[62:63], 0, v[196:197]
	global_load_lds_dwordx4 v[216:217], off
	v_lshl_add_u64 v[216:217], s[64:65], 0, v[198:199]
	s_add_i32 m0, s53, 0x2000
	s_nop 0
	global_load_lds_dwordx4 v[216:217], off
	v_lshl_add_u64 v[216:217], s[62:63], 0, v[194:195]
	s_mov_b32 m0, s25
	s_nop 0
	global_load_lds_dwordx4 v[216:217], off
	s_mov_b32 m0, s26
	s_nop 0
	global_load_lds_dwordx4 v[218:219], off
	s_waitcnt vmcnt(8)
	s_waitcnt lgkmcnt(0)
	s_barrier
; #define PG8_STAGE(bufoff, gbase, voff) do { _Pragma("unroll") for (int _i = 0; _i < 2; ++_i) \
;         __builtin_amdgcn_global_load_lds((const unsigned*)((const char*)(gbase) + (voff)[_i]), (PG8_LAS unsigned*)(lds + (bufoff) + ldsw + _i * 8192), 16, 0, 0); } while (0)
; #define PG8_LDA(dst, b, h) do { _Pragma("unroll") for (int m = 0; m < 4; ++m) _Pragma("unroll") for (int k = 0; k < 2; ++k) dst[m][k] = *(const PG8_LAS bf16x8*)(lds + PG8_SA(b, h) + aoff + m * 2048 + k * 1024); } while (0)
; #define PG8_LDB(dst, b, h) do { _Pragma("unroll") for (int n = 0; n < 2; ++n) _Pragma("unroll") for (int k = 0; k < 2; ++k) dst[n][k] = *(const PG8_LAS bf16x8*)(lds + PG8_SB(b, h) + boff + n * 2048 + k * 1024); } while (0)
; #define PG8_MMA(ai, bj, At, Bt) do { __builtin_amdgcn_s_setprio(1); _Pragma("unroll") for (int m = 0; m < 4; ++m) _Pragma("unroll") for (int n = 0; n < 2; ++n) _Pragma("unroll") for (int k = 0; k < 2; ++k) \
;         acc[ai][bj][m][n] = __builtin_amdgcn_mfma_f32_16x16x32_bf16(Bt[n][k], At[m][k], acc[ai][bj][m][n], 0, 0, 0); __builtin_amdgcn_s_setprio(0); } while (0)
; #define PG8_WAIT_V(n) asm volatile("s_waitcnt vmcnt(" #n ")" ::: "memory")
; #define PG8_WAIT_L(n) asm volatile("s_waitcnt lgkmcnt(" #n ")" ::: "memory")
; #define PG8_BAR __builtin_amdgcn_s_barrier()
; #define PG8_SCHED __builtin_amdgcn_sched_barrier(0)
; template <class Epi, class Sched, bool ALIGN_EPI = false, bool SP2 = false>
; __device__ __forceinline__ void gemm_phase(PG8_LAS unsigned char* lds, const Gemm g, const Sched& S, const Epi& E) {
;     ...
;             PG8_WAIT_V(8); PG8_WAIT_L(0); PG8_BAR; PG8_MMA(1, 0, At, B0); PG8_MMA(1, 1, At, B1); PG8_BAR; PG8_SCHED;
;             PG8_LDB(B0, 1, 0); PG8_LDB(B1, 1, 1); PG8_SCHED; PG8_LDA(At, 1, 0); PG8_STAGE(PG8_SA(0, 1), a2 + hstep, voffA);
;             PG8_WAIT_V(8); PG8_WAIT_L(0); PG8_BAR; PG8_MMA(0, 0, At, B0); PG8_MMA(0, 1, At, B1); PG8_BAR; PG8_SCHED;
	s_setprio 1
	s_waitcnt lgkmcnt(0)
	v_mfma_f32_16x16x32_bf16 v[62:65], v[122:125], v[162:165], 0
	v_mfma_f32_16x16x32_bf16 v[58:61], v[130:133], v[162:165], 0
	v_mfma_f32_16x16x32_bf16 v[46:49], v[122:125], v[170:173], 0
	v_mfma_f32_16x16x32_bf16 v[42:45], v[130:133], v[170:173], 0
	v_mfma_f32_16x16x32_bf16 v[30:33], v[122:125], v[178:181], 0
	v_mfma_f32_16x16x32_bf16 v[26:29], v[130:133], v[178:181], 0
	v_mfma_f32_16x16x32_bf16 v[14:17], v[122:125], v[186:189], 0
	v_mfma_f32_16x16x32_bf16 v[10:13], v[130:133], v[186:189], 0
	v_mfma_f32_16x16x32_bf16 v[62:65], v[126:129], v[166:169], v[62:65]
	v_mfma_f32_16x16x32_bf16 v[58:61], v[134:137], v[166:169], v[58:61]
	v_mfma_f32_16x16x32_bf16 v[46:49], v[126:129], v[174:177], v[46:49]
	v_mfma_f32_16x16x32_bf16 v[42:45], v[134:137], v[174:177], v[42:45]
	v_mfma_f32_16x16x32_bf16 v[30:33], v[126:129], v[182:185], v[30:33]
	v_mfma_f32_16x16x32_bf16 v[26:29], v[134:137], v[182:185], v[26:29]
	v_mfma_f32_16x16x32_bf16 v[14:17], v[126:129], v[208:211], v[14:17]
	v_mfma_f32_16x16x32_bf16 v[10:13], v[134:137], v[208:211], v[10:13]
	s_setprio 0
	s_setprio 1
	v_mfma_f32_16x16x32_bf16 v[54:57], v[138:141], v[162:165], 0
	v_mfma_f32_16x16x32_bf16 v[50:53], v[146:149], v[162:165], 0
	v_mfma_f32_16x16x32_bf16 v[38:41], v[138:141], v[170:173], 0
	v_mfma_f32_16x16x32_bf16 v[34:37], v[146:149], v[170:173], 0
	v_mfma_f32_16x16x32_bf16 v[22:25], v[138:141], v[178:181], 0
	v_mfma_f32_16x16x32_bf16 v[18:21], v[146:149], v[178:181], 0
	v_mfma_f32_16x16x32_bf16 v[6:9], v[138:141], v[186:189], 0
	v_mfma_f32_16x16x32_bf16 v[2:5], v[146:149], v[186:189], 0
	v_mfma_f32_16x16x32_bf16 v[54:57], v[142:145], v[166:169], v[54:57]
	v_mfma_f32_16x16x32_bf16 v[50:53], v[158:161], v[166:169], v[50:53]
	v_mfma_f32_16x16x32_bf16 v[38:41], v[142:145], v[174:177], v[38:41]
	v_mfma_f32_16x16x32_bf16 v[34:37], v[158:161], v[174:177], v[34:37]
	v_mfma_f32_16x16x32_bf16 v[22:25], v[142:145], v[182:185], v[22:25]
	v_mfma_f32_16x16x32_bf16 v[18:21], v[158:161], v[182:185], v[18:21]
	v_mfma_f32_16x16x32_bf16 v[6:9], v[142:145], v[208:211], v[6:9]
	v_mfma_f32_16x16x32_bf16 v[2:5], v[158:161], v[208:211], v[2:5]
	s_setprio 0
	s_barrier
	s_add_i32 s53, 0, 0x18000
	s_add_i32 s64, 0, 0x1c000
	v_add_u32_e32 v134, s53, v239
	v_add_u32_e32 v158, s64, v239
	ds_read_b128 v[122:125], v134
	ds_read_b128 v[126:129], v134 offset:1024
	ds_read_b128 v[130:133], v134 offset:2048
	ds_read_b128 v[134:137], v134 offset:3072
	ds_read_b128 v[138:141], v158
	ds_read_b128 v[142:145], v158 offset:1024
	ds_read_b128 v[146:149], v158 offset:2048
	ds_read_b128 v[158:161], v158 offset:3072
	s_add_u32 s62, s62, 0x40000
	s_addc_u32 s63, s63, 0
	s_mov_b32 m0, s27
	v_lshl_add_u64 v[220:221], s[62:63], 0, v[194:195]
	ds_read_b128 v[162:165], v241 offset:32768
	ds_read_b128 v[166:169], v241 offset:33792
	ds_read_b128 v[170:173], v241 offset:34816
	ds_read_b128 v[174:177], v241 offset:35840
	ds_read_b128 v[178:181], v241 offset:36864
	ds_read_b128 v[182:185], v241 offset:37888
	ds_read_b128 v[186:189], v241 offset:38912
	ds_read_b128 v[208:211], v241 offset:39936
	global_load_lds_dwordx4 v[220:221], off
	v_lshl_add_u64 v[220:221], s[62:63], 0, v[196:197]
	s_mov_b32 m0, s28
	s_nop 0
	global_load_lds_dwordx4 v[220:221], off
	s_waitcnt vmcnt(8)
	s_waitcnt lgkmcnt(0)
	s_barrier
	s_setprio 1
	s_waitcnt lgkmcnt(0)
	v_mfma_f32_16x16x32_bf16 v[154:157], v[122:125], v[162:165], v[154:157]
	v_mfma_f32_16x16x32_bf16 v[150:153], v[130:133], v[162:165], v[150:153]
	v_mfma_f32_16x16x32_bf16 v[110:113], v[122:125], v[170:173], v[110:113]
	v_mfma_f32_16x16x32_bf16 v[106:109], v[130:133], v[170:173], v[106:109]
	v_mfma_f32_16x16x32_bf16 v[94:97], v[122:125], v[178:181], v[94:97]
	v_mfma_f32_16x16x32_bf16 v[90:93], v[130:133], v[178:181], v[90:93]
	v_mfma_f32_16x16x32_bf16 v[78:81], v[122:125], v[186:189], v[78:81]
	v_mfma_f32_16x16x32_bf16 v[74:77], v[130:133], v[186:189], v[74:77]
	v_mfma_f32_16x16x32_bf16 v[154:157], v[126:129], v[166:169], v[154:157]
	v_mfma_f32_16x16x32_bf16 v[150:153], v[134:137], v[166:169], v[150:153]
	v_mfma_f32_16x16x32_bf16 v[110:113], v[126:129], v[174:177], v[110:113]
	v_mfma_f32_16x16x32_bf16 v[106:109], v[134:137], v[174:177], v[106:109]
	v_mfma_f32_16x16x32_bf16 v[94:97], v[126:129], v[182:185], v[94:97]
	v_mfma_f32_16x16x32_bf16 v[90:93], v[134:137], v[182:185], v[90:93]
	v_mfma_f32_16x16x32_bf16 v[78:81], v[126:129], v[208:211], v[78:81]
	v_mfma_f32_16x16x32_bf16 v[74:77], v[134:137], v[208:211], v[74:77]
	s_setprio 0
	s_setprio 1
	v_mfma_f32_16x16x32_bf16 v[118:121], v[138:141], v[162:165], v[118:121]
	v_mfma_f32_16x16x32_bf16 v[114:117], v[146:149], v[162:165], v[114:117]
	v_mfma_f32_16x16x32_bf16 v[102:105], v[138:141], v[170:173], v[102:105]
	v_mfma_f32_16x16x32_bf16 v[98:101], v[146:149], v[170:173], v[98:101]
	v_mfma_f32_16x16x32_bf16 v[86:89], v[138:141], v[178:181], v[86:89]
	v_mfma_f32_16x16x32_bf16 v[82:85], v[146:149], v[178:181], v[82:85]
	v_mfma_f32_16x16x32_bf16 v[70:73], v[138:141], v[186:189], v[70:73]
	v_mfma_f32_16x16x32_bf16 v[66:69], v[146:149], v[186:189], v[66:69]
	v_mfma_f32_16x16x32_bf16 v[118:121], v[142:145], v[166:169], v[118:121]
	v_mfma_f32_16x16x32_bf16 v[114:117], v[158:161], v[166:169], v[114:117]
	v_mfma_f32_16x16x32_bf16 v[102:105], v[142:145], v[174:177], v[102:105]
	v_mfma_f32_16x16x32_bf16 v[98:101], v[158:161], v[174:177], v[98:101]
	v_mfma_f32_16x16x32_bf16 v[86:89], v[142:145], v[182:185], v[86:89]
	v_mfma_f32_16x16x32_bf16 v[82:85], v[158:161], v[182:185], v[82:85]
	v_mfma_f32_16x16x32_bf16 v[70:73], v[142:145], v[208:211], v[70:73]
	v_mfma_f32_16x16x32_bf16 v[66:69], v[158:161], v[208:211], v[66:69]
	s_setprio 0
	s_barrier
; #define PG8_STAGE(bufoff, gbase, voff) do { _Pragma("unroll") for (int _i = 0; _i < 2; ++_i) \
;         __builtin_amdgcn_global_load_lds((const unsigned*)((const char*)(gbase) + (voff)[_i]), (PG8_LAS unsigned*)(lds + (bufoff) + ldsw + _i * 8192), 16, 0, 0); } while (0)
; #define PG8_LDA(dst, b, h) do { _Pragma("unroll") for (int m = 0; m < 4; ++m) _Pragma("unroll") for (int k = 0; k < 2; ++k) dst[m][k] = *(const PG8_LAS bf16x8*)(lds + PG8_SA(b, h) + aoff + m * 2048 + k * 1024); } while (0)
; #define PG8_MMA(ai, bj, At, Bt) do { __builtin_amdgcn_s_setprio(1); _Pragma("unroll") for (int m = 0; m < 4; ++m) _Pragma("unroll") for (int n = 0; n < 2; ++n) _Pragma("unroll") for (int k = 0; k < 2; ++k) \
;         acc[ai][bj][m][n] = __builtin_amdgcn_mfma_f32_16x16x32_bf16(Bt[n][k], At[m][k], acc[ai][bj][m][n], 0, 0, 0); __builtin_amdgcn_s_setprio(0); } while (0)
; #define PG8_WAIT_V(n) asm volatile("s_waitcnt vmcnt(" #n ")" ::: "memory")
; #define PG8_WAIT_L(n) asm volatile("s_waitcnt lgkmcnt(" #n ")" ::: "memory")
; #define PG8_BAR __builtin_amdgcn_s_barrier()
; #define PG8_SCHED __builtin_amdgcn_sched_barrier(0)
; template <class Epi, class Sched, bool ALIGN_EPI = false, bool SP2 = false>
; __device__ __forceinline__ void gemm_phase(PG8_LAS unsigned char* lds, const Gemm g, const Sched& S, const Epi& E) {
;     ...
;         for (int t = 0; t < nt; t += 2) {
;     ...
;             PG8_LDA(At, 1, 1); PG8_STAGE(PG8_SB(1, 0), b3, voffB); PG8_STAGE(PG8_SB(1, 1), b3 + hstep, voffB); PG8_STAGE(PG8_SA(1, 0), a3, voffA);
;             PG8_WAIT_V(8); PG8_WAIT_L(0); PG8_BAR; PG8_MMA(1, 0, At, B0); PG8_MMA(1, 1, At, B1); PG8_BAR; PG8_SCHED;
	s_add_i32 s53, s53, s24
	v_lshl_add_u64 v[212:213], v[212:213], 0, s[8:9]
	s_mov_b32 m0, s53
	ds_read_b128 v[162:165], v241 offset:49152
	ds_read_b128 v[166:169], v241 offset:50176
	ds_read_b128 v[170:173], v241 offset:51200
	ds_read_b128 v[174:177], v241 offset:52224
	ds_read_b128 v[178:181], v241 offset:53248
	ds_read_b128 v[182:185], v241 offset:54272
	ds_read_b128 v[186:189], v241 offset:55296
	ds_read_b128 v[208:211], v241 offset:56320
	global_load_lds_dwordx4 v[212:213], off
	s_add_i32 m0, s53, 0x2000
	s_add_u32 s60, s60, 0x40080
	v_lshl_add_u64 v[212:213], v[214:215], 0, s[8:9]
	s_addc_u32 s61, s61, 0
	s_add_i32 s53, s64, s24
	global_load_lds_dwordx4 v[212:213], off
	v_lshl_add_u64 v[212:213], s[60:61], 0, v[0:1]
	s_mov_b32 m0, s53
	s_nop 0
	global_load_lds_dwordx4 v[212:213], off
	v_lshl_add_u64 v[212:213], s[60:61], 0, v[198:199]
	s_add_i32 m0, s53, 0x2000
	s_nop 0
	global_load_lds_dwordx4 v[212:213], off
	v_lshl_add_u64 v[212:213], v[216:217], 0, s[8:9]
	s_mov_b32 m0, s29
	s_nop 0
	global_load_lds_dwordx4 v[212:213], off
	v_lshl_add_u64 v[212:213], v[218:219], 0, s[8:9]
	s_mov_b32 m0, s57
	s_nop 0
	global_load_lds_dwordx4 v[212:213], off
	s_waitcnt vmcnt(8)
	s_waitcnt lgkmcnt(0)
	s_barrier
	s_setprio 1
	s_waitcnt lgkmcnt(0)
	v_mfma_f32_16x16x32_bf16 v[62:65], v[122:125], v[162:165], v[62:65]
	v_mfma_f32_16x16x32_bf16 v[58:61], v[130:133], v[162:165], v[58:61]
	v_mfma_f32_16x16x32_bf16 v[46:49], v[122:125], v[170:173], v[46:49]
	v_mfma_f32_16x16x32_bf16 v[42:45], v[130:133], v[170:173], v[42:45]
	v_mfma_f32_16x16x32_bf16 v[30:33], v[122:125], v[178:181], v[30:33]
	v_mfma_f32_16x16x32_bf16 v[26:29], v[130:133], v[178:181], v[26:29]
	v_mfma_f32_16x16x32_bf16 v[14:17], v[122:125], v[186:189], v[14:17]
	v_mfma_f32_16x16x32_bf16 v[10:13], v[130:133], v[186:189], v[10:13]
	v_mfma_f32_16x16x32_bf16 v[62:65], v[126:129], v[166:169], v[62:65]
	v_mfma_f32_16x16x32_bf16 v[58:61], v[134:137], v[166:169], v[58:61]
	v_mfma_f32_16x16x32_bf16 v[46:49], v[126:129], v[174:177], v[46:49]
	v_mfma_f32_16x16x32_bf16 v[42:45], v[134:137], v[174:177], v[42:45]
	v_mfma_f32_16x16x32_bf16 v[30:33], v[126:129], v[182:185], v[30:33]
	v_mfma_f32_16x16x32_bf16 v[26:29], v[134:137], v[182:185], v[26:29]
	v_mfma_f32_16x16x32_bf16 v[14:17], v[126:129], v[208:211], v[14:17]
	v_mfma_f32_16x16x32_bf16 v[10:13], v[134:137], v[208:211], v[10:13]
	s_setprio 0
	s_setprio 1
	v_mfma_f32_16x16x32_bf16 v[54:57], v[138:141], v[162:165], v[54:57]
	v_mfma_f32_16x16x32_bf16 v[50:53], v[146:149], v[162:165], v[50:53]
	v_mfma_f32_16x16x32_bf16 v[38:41], v[138:141], v[170:173], v[38:41]
	v_mfma_f32_16x16x32_bf16 v[34:37], v[146:149], v[170:173], v[34:37]
	v_mfma_f32_16x16x32_bf16 v[22:25], v[138:141], v[178:181], v[22:25]
	v_mfma_f32_16x16x32_bf16 v[18:21], v[146:149], v[178:181], v[18:21]
	v_mfma_f32_16x16x32_bf16 v[6:9], v[138:141], v[186:189], v[6:9]
	v_mfma_f32_16x16x32_bf16 v[2:5], v[146:149], v[186:189], v[2:5]
	v_mfma_f32_16x16x32_bf16 v[54:57], v[142:145], v[166:169], v[54:57]
	v_mfma_f32_16x16x32_bf16 v[50:53], v[158:161], v[166:169], v[50:53]
	v_mfma_f32_16x16x32_bf16 v[38:41], v[142:145], v[174:177], v[38:41]
	v_mfma_f32_16x16x32_bf16 v[34:37], v[158:161], v[174:177], v[34:37]
	v_mfma_f32_16x16x32_bf16 v[22:25], v[142:145], v[182:185], v[22:25]
	v_mfma_f32_16x16x32_bf16 v[18:21], v[158:161], v[182:185], v[18:21]
	v_mfma_f32_16x16x32_bf16 v[6:9], v[142:145], v[208:211], v[6:9]
	v_mfma_f32_16x16x32_bf16 v[2:5], v[158:161], v[208:211], v[2:5]
	s_setprio 0
	s_barrier
	s_add_i32 s52, s52, 2
	s_add_u32 s18, s18, 0x100
	s_addc_u32 s19, s19, 0
	s_add_u32 s45, s45, 0x100
	s_addc_u32 s47, s47, 0
	s_cmp_gt_u32 s52, 13

; template <class Epi, class Sched, bool ALIGN_EPI = false, bool SP2 = false>
; __device__ __forceinline__ void gemm_phase(PG8_LAS unsigned char* lds, const Gemm g, const Sched& S, const Epi& E) {
;     ...
;         const bool has_next = S.next(ui + 1, nxt);
;         const char* nA = has_next ? (const char*)g.A + (size_t)nxt.pm * tstep : cA; const char* nB = has_next ? (const char*)g.Bt + (size_t)nxt.pn * tstep : cB;
;     ...
; #pragma unroll
;         for (int a = 0; a < 2; ++a)
; #pragma unroll
;             for (int b = 0; b < 2; ++b)
; #pragma unroll
;                 for (int m = 0; m < 4; ++m)
; #pragma unroll
;                     for (int n = 0; n < 2; ++n) acc[a][b][m][n] = (f32x4){0.f, 0.f, 0.f, 0.f};
.LBB0_521:
	s_ashr_i32 s45, s44, 31
	s_lshl_b64 s[30:31], s[44:45], 19
	s_add_u32 s48, s98, s30
	s_addc_u32 s49, s99, s31
	s_and_b64 s[30:31], s[46:47], exec
	s_cselect_b32 s30, s49, s19
	s_cselect_b32 s31, s48, s18
	s_ashr_i32 s43, s42, 31
	s_lshl_b64 s[34:35], s[42:43], 19
	s_add_u32 s50, s68, s34
	s_addc_u32 s51, s69, s35
	s_and_b64 s[34:35], s[46:47], exec
	s_cselect_b32 s34, s51, s59
	s_cselect_b32 s35, s50, s58
	s_add_u32 s18, s18, 0x40080
	s_addc_u32 s19, s19, 0
	s_add_u32 s43, s58, 0x100

; template <class Epi, class Sched, bool ALIGN_EPI = false, bool SP2 = false>
; __device__ __forceinline__ void gemm_phase(PG8_LAS unsigned char* lds, const Gemm g, const Sched& S, const Epi& E) {
;     ...
;         for (int t = 0; t < nt; t += 2) {
;     ...
; #pragma unroll
;         for (int a = 0; a < 2; ++a)
; #pragma unroll
;             for (int b = 0; b < 2; ++b)
; #pragma unroll
;                 for (int m = 0; m < 4; ++m)
; #pragma unroll
;                     for (int n = 0; n < 2; ++n) acc[a][b][m][n] = (f32x4){0.f, 0.f, 0.f, 0.f};
	s_addc_u32 s45, s59, 0
	s_mov_b32 s52, -2


; template <class Epi, class Sched, bool ALIGN_EPI = false, bool SP2 = false>
; __device__ __forceinline__ void gemm_phase(PG8_LAS unsigned char* lds, const Gemm g, const Sched& S, const Epi& E) {
;     ...
; #pragma unroll
;         for (int a = 0; a < 2; ++a)
; #pragma unroll
;             for (int b = 0; b < 2; ++b)
; #pragma unroll
;                 for (int m = 0; m < 4; ++m)
; #pragma unroll
;                     for (int n = 0; n < 2; ++n) acc[a][b][m][n] = (f32x4){0.f, 0.f, 0.f, 0.f};
	s_waitcnt lgkmcnt(0)


; template <class Epi, class Sched, bool ALIGN_EPI = false, bool SP2 = false>
; __device__ __forceinline__ void gemm_phase(PG8_LAS unsigned char* lds, const Gemm g, const Sched& S, const Epi& E) {
;     ...
; #pragma unroll
;         for (int a = 0; a < 2; ++a)
; #pragma unroll
;             for (int b = 0; b < 2; ++b)
; #pragma unroll
;                 for (int m = 0; m < 4; ++m)
; #pragma unroll
;                     for (int n = 0; n < 2; ++n) acc[a][b][m][n] = (f32x4){0.f, 0.f, 0.f, 0.f};
	s_waitcnt vmcnt(0)


; #define PG8_STAGE(bufoff, gbase, voff) do { _Pragma("unroll") for (int _i = 0; _i < 2; ++_i) \
;         __builtin_amdgcn_global_load_lds((const unsigned*)((const char*)(gbase) + (voff)[_i]), (PG8_LAS unsigned*)(lds + (bufoff) + ldsw + _i * 8192), 16, 0, 0); } while (0)
; #define PG8_LDA(dst, b, h) do { _Pragma("unroll") for (int m = 0; m < 4; ++m) _Pragma("unroll") for (int k = 0; k < 2; ++k) dst[m][k] = *(const PG8_LAS bf16x8*)(lds + PG8_SA(b, h) + aoff + m * 2048 + k * 1024); } while (0)
; #define PG8_LDB(dst, b, h) do { _Pragma("unroll") for (int n = 0; n < 2; ++n) _Pragma("unroll") for (int k = 0; k < 2; ++k) dst[n][k] = *(const PG8_LAS bf16x8*)(lds + PG8_SB(b, h) + boff + n * 2048 + k * 1024); } while (0)
; #define PG8_MMA(ai, bj, At, Bt) do { __builtin_amdgcn_s_setprio(1); _Pragma("unroll") for (int m = 0; m < 4; ++m) _Pragma("unroll") for (int n = 0; n < 2; ++n) _Pragma("unroll") for (int k = 0; k < 2; ++k) \
;         acc[ai][bj][m][n] = __builtin_amdgcn_mfma_f32_16x16x32_bf16(Bt[n][k], At[m][k], acc[ai][bj][m][n], 0, 0, 0); __builtin_amdgcn_s_setprio(0); } while (0)
; #define PG8_WAIT_V(n) asm volatile("s_waitcnt vmcnt(" #n ")" ::: "memory")
; #define PG8_WAIT_L(n) asm volatile("s_waitcnt lgkmcnt(" #n ")" ::: "memory")
; #define PG8_BAR __builtin_amdgcn_s_barrier()
; #define PG8_SCHED __builtin_amdgcn_sched_barrier(0)
; template <class Epi, class Sched, bool ALIGN_EPI = false, bool SP2 = false>
; __device__ __forceinline__ void gemm_phase(PG8_LAS unsigned char* lds, const Gemm g, const Sched& S, const Epi& E) {
;     ...
;             const bool last = (t == nt - 2);
;             const char* a1 = cA + (size_t)(t + 1) * kstep;
;             const char* a2 = last ? nA : cA + (size_t)(t + 2) * kstep; const char* b2 = last ? nB : cB + (size_t)(t + 2) * kstep;
;             const char* a3 = a2 + kstep; const char* b3 = b2 + kstep;
;             if (last && has_next) S.a_ready(nxt);
;             if constexpr (SP2) {
;             PG8_LDB(B0, 0, 0); PG8_LDB(B1, 0, 1); PG8_SCHED; PG8_LDA(At, 0, 0); PG8_STAGE(PG8_SA(1, 1), a1 + hstep, voffA);
;             PG8_WAIT_V(8); PG8_WAIT_L(0); PG8_BAR; PG8_MMA(0, 0, At, B0); PG8_MMA(0, 1, At, B1); PG8_BAR; PG8_SCHED;
;             PG8_LDA(At, 0, 1); PG8_STAGE(PG8_SB(0, 0), b2, voffB); PG8_STAGE(PG8_SB(0, 1), b2 + hstep, voffB); PG8_STAGE(PG8_SA(0, 0), a2, voffA);
	s_add_u32 s53, s18, 0xfffc0080
	s_addc_u32 s58, s19, -1
	s_add_i32 s62, 0, 0x10000
	s_cmp_eq_u32 s52, 12
	s_cselect_b32 s61, s30, s58
	s_cselect_b32 s60, s31, s53
	s_cselect_b32 s59, s34, s45
	s_cselect_b32 s58, s35, s43
	s_add_i32 s53, 0, 0x14000
	v_add_u32_e32 v156, s62, v149
	v_add_u32_e32 v172, s53, v149
	ds_read_b128 v[140:143], v156
	ds_read_b128 v[144:147], v156 offset:1024
	ds_read_b128 v[152:155], v156 offset:2048
	ds_read_b128 v[156:159], v156 offset:3072
	ds_read_b128 v[160:163], v172
	ds_read_b128 v[164:167], v172 offset:1024
	ds_read_b128 v[168:171], v172 offset:2048
	ds_read_b128 v[172:175], v172 offset:3072
	v_lshl_add_u64 v[188:189], s[18:19], 0, v[136:137]
	s_add_i32 m0, s25, 0xc000
	ds_read_b128 v[176:179], v151
	ds_read_b128 v[180:183], v151 offset:1024
	ds_read_b128 v[184:187], v151 offset:2048
	ds_read_b128 v[194:197], v151 offset:3072
	ds_read_b128 v[198:201], v151 offset:4096
	ds_read_b128 v[202:205], v151 offset:5120
	ds_read_b128 v[206:209], v151 offset:6144
	ds_read_b128 v[210:213], v151 offset:7168
	global_load_lds_dwordx4 v[188:189], off
	v_lshl_add_u64 v[188:189], s[18:19], 0, v[138:139]
	s_add_i32 m0, s25, 0xe000
	s_nop 0
	global_load_lds_dwordx4 v[188:189], off
	s_waitcnt vmcnt(8)
	s_waitcnt lgkmcnt(0)
	s_barrier
	s_setprio 1
	s_waitcnt lgkmcnt(0)
	v_mfma_f32_16x16x32_bf16 v[126:129], v[140:143], v[176:179], 0
	v_mfma_f32_16x16x32_bf16 v[122:125], v[152:155], v[176:179], 0
	v_mfma_f32_16x16x32_bf16 v[118:121], v[140:143], v[184:187], 0
	v_mfma_f32_16x16x32_bf16 v[110:113], v[152:155], v[184:187], 0
	v_mfma_f32_16x16x32_bf16 v[94:97], v[140:143], v[198:201], 0
	v_mfma_f32_16x16x32_bf16 v[90:93], v[152:155], v[198:201], 0
	v_mfma_f32_16x16x32_bf16 v[78:81], v[140:143], v[206:209], 0
	v_mfma_f32_16x16x32_bf16 v[74:77], v[152:155], v[206:209], 0
	v_mfma_f32_16x16x32_bf16 v[126:129], v[144:147], v[180:183], v[126:129]
	v_mfma_f32_16x16x32_bf16 v[122:125], v[156:159], v[180:183], v[122:125]
	v_mfma_f32_16x16x32_bf16 v[118:121], v[144:147], v[194:197], v[118:121]
	v_mfma_f32_16x16x32_bf16 v[110:113], v[156:159], v[194:197], v[110:113]
	v_mfma_f32_16x16x32_bf16 v[94:97], v[144:147], v[202:205], v[94:97]
	v_mfma_f32_16x16x32_bf16 v[90:93], v[156:159], v[202:205], v[90:93]
	v_mfma_f32_16x16x32_bf16 v[78:81], v[144:147], v[210:213], v[78:81]
	v_mfma_f32_16x16x32_bf16 v[74:77], v[156:159], v[210:213], v[74:77]
	s_setprio 0
	s_setprio 1
	v_mfma_f32_16x16x32_bf16 v[114:117], v[160:163], v[176:179], 0
	v_mfma_f32_16x16x32_bf16 v[106:109], v[168:171], v[176:179], 0
	v_mfma_f32_16x16x32_bf16 v[102:105], v[160:163], v[184:187], 0
	v_mfma_f32_16x16x32_bf16 v[98:101], v[168:171], v[184:187], 0
	v_mfma_f32_16x16x32_bf16 v[86:89], v[160:163], v[198:201], 0
	v_mfma_f32_16x16x32_bf16 v[82:85], v[168:171], v[198:201], 0
	v_mfma_f32_16x16x32_bf16 v[70:73], v[160:163], v[206:209], 0
	v_mfma_f32_16x16x32_bf16 v[66:69], v[168:171], v[206:209], 0
	v_mfma_f32_16x16x32_bf16 v[114:117], v[164:167], v[180:183], v[114:117]
	v_mfma_f32_16x16x32_bf16 v[106:109], v[172:175], v[180:183], v[106:109]
	v_mfma_f32_16x16x32_bf16 v[102:105], v[164:167], v[194:197], v[102:105]
	v_mfma_f32_16x16x32_bf16 v[98:101], v[172:175], v[194:197], v[98:101]
	v_mfma_f32_16x16x32_bf16 v[86:89], v[164:167], v[202:205], v[86:89]
	v_mfma_f32_16x16x32_bf16 v[82:85], v[172:175], v[202:205], v[82:85]
	v_mfma_f32_16x16x32_bf16 v[70:73], v[164:167], v[210:213], v[70:73]
	v_mfma_f32_16x16x32_bf16 v[66:69], v[172:175], v[210:213], v[66:69]
	s_setprio 0
	s_barrier
	s_add_i32 s62, s62, s24
	v_lshl_add_u64 v[188:189], s[58:59], 0, v[0:1]
	s_mov_b32 m0, s62
	ds_read_b128 v[176:179], v151 offset:16384
	ds_read_b128 v[180:183], v151 offset:17408
	ds_read_b128 v[184:187], v151 offset:18432
	ds_read_b128 v[194:197], v151 offset:19456
	ds_read_b128 v[198:201], v151 offset:20480
	ds_read_b128 v[202:205], v151 offset:21504
	ds_read_b128 v[206:209], v151 offset:22528
	ds_read_b128 v[210:213], v151 offset:23552
	global_load_lds_dwordx4 v[188:189], off
	s_add_i32 m0, s62, 0x2000
	s_add_u32 s62, s58, 0x40000
	v_lshl_add_u64 v[214:215], s[58:59], 0, v[134:135]
	s_addc_u32 s63, s59, 0
	s_add_i32 s53, s53, s24
	global_load_lds_dwordx4 v[214:215], off
	v_lshl_add_u64 v[216:217], s[62:63], 0, v[0:1]
	s_mov_b32 m0, s53
	v_lshl_add_u64 v[218:219], s[60:61], 0, v[132:133]
	global_load_lds_dwordx4 v[216:217], off
	v_lshl_add_u64 v[216:217], s[62:63], 0, v[134:135]
	s_add_i32 m0, s53, 0x2000
	s_nop 0
	global_load_lds_dwordx4 v[216:217], off
	v_lshl_add_u64 v[216:217], s[60:61], 0, v[130:131]
	s_mov_b32 m0, s25
	s_nop 0
	global_load_lds_dwordx4 v[216:217], off
	s_mov_b32 m0, s26
	s_nop 0
	global_load_lds_dwordx4 v[218:219], off
	s_waitcnt vmcnt(8)
	s_waitcnt lgkmcnt(0)
	s_barrier
; #define PG8_STAGE(bufoff, gbase, voff) do { _Pragma("unroll") for (int _i = 0; _i < 2; ++_i) \
;         __builtin_amdgcn_global_load_lds((const unsigned*)((const char*)(gbase) + (voff)[_i]), (PG8_LAS unsigned*)(lds + (bufoff) + ldsw + _i * 8192), 16, 0, 0); } while (0)
; #define PG8_LDA(dst, b, h) do { _Pragma("unroll") for (int m = 0; m < 4; ++m) _Pragma("unroll") for (int k = 0; k < 2; ++k) dst[m][k] = *(const PG8_LAS bf16x8*)(lds + PG8_SA(b, h) + aoff + m * 2048 + k * 1024); } while (0)
; #define PG8_LDB(dst, b, h) do { _Pragma("unroll") for (int n = 0; n < 2; ++n) _Pragma("unroll") for (int k = 0; k < 2; ++k) dst[n][k] = *(const PG8_LAS bf16x8*)(lds + PG8_SB(b, h) + boff + n * 2048 + k * 1024); } while (0)
; #define PG8_MMA(ai, bj, At, Bt) do { __builtin_amdgcn_s_setprio(1); _Pragma("unroll") for (int m = 0; m < 4; ++m) _Pragma("unroll") for (int n = 0; n < 2; ++n) _Pragma("unroll") for (int k = 0; k < 2; ++k) \
;         acc[ai][bj][m][n] = __builtin_amdgcn_mfma_f32_16x16x32_bf16(Bt[n][k], At[m][k], acc[ai][bj][m][n], 0, 0, 0); __builtin_amdgcn_s_setprio(0); } while (0)
; #define PG8_WAIT_V(n) asm volatile("s_waitcnt vmcnt(" #n ")" ::: "memory")
; #define PG8_WAIT_L(n) asm volatile("s_waitcnt lgkmcnt(" #n ")" ::: "memory")
; #define PG8_BAR __builtin_amdgcn_s_barrier()
; #define PG8_SCHED __builtin_amdgcn_sched_barrier(0)
; template <class Epi, class Sched, bool ALIGN_EPI = false, bool SP2 = false>
; __device__ __forceinline__ void gemm_phase(PG8_LAS unsigned char* lds, const Gemm g, const Sched& S, const Epi& E) {
;     ...
;             PG8_WAIT_V(8); PG8_WAIT_L(0); PG8_BAR; PG8_MMA(1, 0, At, B0); PG8_MMA(1, 1, At, B1); PG8_BAR; PG8_SCHED;
;             PG8_LDB(B0, 1, 0); PG8_LDB(B1, 1, 1); PG8_SCHED; PG8_LDA(At, 1, 0); PG8_STAGE(PG8_SA(0, 1), a2 + hstep, voffA);
;             PG8_WAIT_V(8); PG8_WAIT_L(0); PG8_BAR; PG8_MMA(0, 0, At, B0); PG8_MMA(0, 1, At, B1); PG8_BAR; PG8_SCHED;
	s_setprio 1
	s_waitcnt lgkmcnt(0)
	v_mfma_f32_16x16x32_bf16 v[62:65], v[140:143], v[176:179], 0
	v_mfma_f32_16x16x32_bf16 v[58:61], v[152:155], v[176:179], 0
	v_mfma_f32_16x16x32_bf16 v[46:49], v[140:143], v[184:187], 0
	v_mfma_f32_16x16x32_bf16 v[42:45], v[152:155], v[184:187], 0
	v_mfma_f32_16x16x32_bf16 v[30:33], v[140:143], v[198:201], 0
	v_mfma_f32_16x16x32_bf16 v[26:29], v[152:155], v[198:201], 0
	v_mfma_f32_16x16x32_bf16 v[14:17], v[140:143], v[206:209], 0
	v_mfma_f32_16x16x32_bf16 v[10:13], v[152:155], v[206:209], 0
	v_mfma_f32_16x16x32_bf16 v[62:65], v[144:147], v[180:183], v[62:65]
	v_mfma_f32_16x16x32_bf16 v[58:61], v[156:159], v[180:183], v[58:61]
	v_mfma_f32_16x16x32_bf16 v[46:49], v[144:147], v[194:197], v[46:49]
	v_mfma_f32_16x16x32_bf16 v[42:45], v[156:159], v[194:197], v[42:45]
	v_mfma_f32_16x16x32_bf16 v[30:33], v[144:147], v[202:205], v[30:33]
	v_mfma_f32_16x16x32_bf16 v[26:29], v[156:159], v[202:205], v[26:29]
	v_mfma_f32_16x16x32_bf16 v[14:17], v[144:147], v[210:213], v[14:17]
	v_mfma_f32_16x16x32_bf16 v[10:13], v[156:159], v[210:213], v[10:13]
	s_setprio 0
	s_setprio 1
	v_mfma_f32_16x16x32_bf16 v[54:57], v[160:163], v[176:179], 0
	v_mfma_f32_16x16x32_bf16 v[50:53], v[168:171], v[176:179], 0
	v_mfma_f32_16x16x32_bf16 v[38:41], v[160:163], v[184:187], 0
	v_mfma_f32_16x16x32_bf16 v[34:37], v[168:171], v[184:187], 0
	v_mfma_f32_16x16x32_bf16 v[22:25], v[160:163], v[198:201], 0
	v_mfma_f32_16x16x32_bf16 v[18:21], v[168:171], v[198:201], 0
	v_mfma_f32_16x16x32_bf16 v[6:9], v[160:163], v[206:209], 0
	v_mfma_f32_16x16x32_bf16 v[2:5], v[168:171], v[206:209], 0
	v_mfma_f32_16x16x32_bf16 v[54:57], v[164:167], v[180:183], v[54:57]
	v_mfma_f32_16x16x32_bf16 v[50:53], v[172:175], v[180:183], v[50:53]
	v_mfma_f32_16x16x32_bf16 v[38:41], v[164:167], v[194:197], v[38:41]
	v_mfma_f32_16x16x32_bf16 v[34:37], v[172:175], v[194:197], v[34:37]
	v_mfma_f32_16x16x32_bf16 v[22:25], v[164:167], v[202:205], v[22:25]
	v_mfma_f32_16x16x32_bf16 v[18:21], v[172:175], v[202:205], v[18:21]
	v_mfma_f32_16x16x32_bf16 v[6:9], v[164:167], v[210:213], v[6:9]
	v_mfma_f32_16x16x32_bf16 v[2:5], v[172:175], v[210:213], v[2:5]
	s_setprio 0
	s_barrier
	s_add_i32 s53, 0, 0x18000
	s_add_i32 s62, 0, 0x1c000
	v_add_u32_e32 v156, s53, v149
	v_add_u32_e32 v172, s62, v149
	ds_read_b128 v[140:143], v156
	ds_read_b128 v[144:147], v156 offset:1024
	ds_read_b128 v[152:155], v156 offset:2048
	ds_read_b128 v[156:159], v156 offset:3072
	ds_read_b128 v[160:163], v172
	ds_read_b128 v[164:167], v172 offset:1024
	ds_read_b128 v[168:171], v172 offset:2048
	ds_read_b128 v[172:175], v172 offset:3072
	s_add_u32 s60, s60, 0x40000
	s_addc_u32 s61, s61, 0
	s_mov_b32 m0, s27
	v_lshl_add_u64 v[220:221], s[60:61], 0, v[130:131]
	ds_read_b128 v[176:179], v151 offset:32768
	ds_read_b128 v[180:183], v151 offset:33792
	ds_read_b128 v[184:187], v151 offset:34816
	ds_read_b128 v[194:197], v151 offset:35840
	ds_read_b128 v[198:201], v151 offset:36864
	ds_read_b128 v[202:205], v151 offset:37888
	ds_read_b128 v[206:209], v151 offset:38912
	ds_read_b128 v[210:213], v151 offset:39936
	global_load_lds_dwordx4 v[220:221], off
	v_lshl_add_u64 v[220:221], s[60:61], 0, v[132:133]
	s_mov_b32 m0, s28
	s_nop 0
	global_load_lds_dwordx4 v[220:221], off
	s_waitcnt vmcnt(8)
	s_waitcnt lgkmcnt(0)
	s_barrier
	s_setprio 1
	s_waitcnt lgkmcnt(0)
	v_mfma_f32_16x16x32_bf16 v[126:129], v[140:143], v[176:179], v[126:129]
	v_mfma_f32_16x16x32_bf16 v[122:125], v[152:155], v[176:179], v[122:125]
	v_mfma_f32_16x16x32_bf16 v[118:121], v[140:143], v[184:187], v[118:121]
	v_mfma_f32_16x16x32_bf16 v[110:113], v[152:155], v[184:187], v[110:113]
	v_mfma_f32_16x16x32_bf16 v[94:97], v[140:143], v[198:201], v[94:97]
	v_mfma_f32_16x16x32_bf16 v[90:93], v[152:155], v[198:201], v[90:93]
	v_mfma_f32_16x16x32_bf16 v[78:81], v[140:143], v[206:209], v[78:81]
	v_mfma_f32_16x16x32_bf16 v[74:77], v[152:155], v[206:209], v[74:77]
	v_mfma_f32_16x16x32_bf16 v[126:129], v[144:147], v[180:183], v[126:129]
	v_mfma_f32_16x16x32_bf16 v[122:125], v[156:159], v[180:183], v[122:125]
	v_mfma_f32_16x16x32_bf16 v[118:121], v[144:147], v[194:197], v[118:121]
	v_mfma_f32_16x16x32_bf16 v[110:113], v[156:159], v[194:197], v[110:113]
	v_mfma_f32_16x16x32_bf16 v[94:97], v[144:147], v[202:205], v[94:97]
	v_mfma_f32_16x16x32_bf16 v[90:93], v[156:159], v[202:205], v[90:93]
	v_mfma_f32_16x16x32_bf16 v[78:81], v[144:147], v[210:213], v[78:81]
	v_mfma_f32_16x16x32_bf16 v[74:77], v[156:159], v[210:213], v[74:77]
	s_setprio 0
	s_setprio 1
	v_mfma_f32_16x16x32_bf16 v[114:117], v[160:163], v[176:179], v[114:117]
	v_mfma_f32_16x16x32_bf16 v[106:109], v[168:171], v[176:179], v[106:109]
	v_mfma_f32_16x16x32_bf16 v[102:105], v[160:163], v[184:187], v[102:105]
	v_mfma_f32_16x16x32_bf16 v[98:101], v[168:171], v[184:187], v[98:101]
	v_mfma_f32_16x16x32_bf16 v[86:89], v[160:163], v[198:201], v[86:89]
	v_mfma_f32_16x16x32_bf16 v[82:85], v[168:171], v[198:201], v[82:85]
	v_mfma_f32_16x16x32_bf16 v[70:73], v[160:163], v[206:209], v[70:73]
	v_mfma_f32_16x16x32_bf16 v[66:69], v[168:171], v[206:209], v[66:69]
	v_mfma_f32_16x16x32_bf16 v[114:117], v[164:167], v[180:183], v[114:117]
	v_mfma_f32_16x16x32_bf16 v[106:109], v[172:175], v[180:183], v[106:109]
	v_mfma_f32_16x16x32_bf16 v[102:105], v[164:167], v[194:197], v[102:105]
	v_mfma_f32_16x16x32_bf16 v[98:101], v[172:175], v[194:197], v[98:101]
	v_mfma_f32_16x16x32_bf16 v[86:89], v[164:167], v[202:205], v[86:89]
	v_mfma_f32_16x16x32_bf16 v[82:85], v[172:175], v[202:205], v[82:85]
	v_mfma_f32_16x16x32_bf16 v[70:73], v[164:167], v[210:213], v[70:73]
	v_mfma_f32_16x16x32_bf16 v[66:69], v[172:175], v[210:213], v[66:69]
	s_setprio 0
	s_barrier
; #define PG8_STAGE(bufoff, gbase, voff) do { _Pragma("unroll") for (int _i = 0; _i < 2; ++_i) \
;         __builtin_amdgcn_global_load_lds((const unsigned*)((const char*)(gbase) + (voff)[_i]), (PG8_LAS unsigned*)(lds + (bufoff) + ldsw + _i * 8192), 16, 0, 0); } while (0)
; #define PG8_LDA(dst, b, h) do { _Pragma("unroll") for (int m = 0; m < 4; ++m) _Pragma("unroll") for (int k = 0; k < 2; ++k) dst[m][k] = *(const PG8_LAS bf16x8*)(lds + PG8_SA(b, h) + aoff + m * 2048 + k * 1024); } while (0)
; #define PG8_MMA(ai, bj, At, Bt) do { __builtin_amdgcn_s_setprio(1); _Pragma("unroll") for (int m = 0; m < 4; ++m) _Pragma("unroll") for (int n = 0; n < 2; ++n) _Pragma("unroll") for (int k = 0; k < 2; ++k) \
;         acc[ai][bj][m][n] = __builtin_amdgcn_mfma_f32_16x16x32_bf16(Bt[n][k], At[m][k], acc[ai][bj][m][n], 0, 0, 0); __builtin_amdgcn_s_setprio(0); } while (0)
; #define PG8_WAIT_V(n) asm volatile("s_waitcnt vmcnt(" #n ")" ::: "memory")
; #define PG8_WAIT_L(n) asm volatile("s_waitcnt lgkmcnt(" #n ")" ::: "memory")
; #define PG8_BAR __builtin_amdgcn_s_barrier()
; #define PG8_SCHED __builtin_amdgcn_sched_barrier(0)
; template <class Epi, class Sched, bool ALIGN_EPI = false, bool SP2 = false>
; __device__ __forceinline__ void gemm_phase(PG8_LAS unsigned char* lds, const Gemm g, const Sched& S, const Epi& E) {
;     ...
;         for (int t = 0; t < nt; t += 2) {
;     ...
;             PG8_LDA(At, 1, 1); PG8_STAGE(PG8_SB(1, 0), b3, voffB); PG8_STAGE(PG8_SB(1, 1), b3 + hstep, voffB); PG8_STAGE(PG8_SA(1, 0), a3, voffA);
;             PG8_WAIT_V(8); PG8_WAIT_L(0); PG8_BAR; PG8_MMA(1, 0, At, B0); PG8_MMA(1, 1, At, B1); PG8_BAR; PG8_SCHED;
	s_add_i32 s53, s53, s24
	v_lshl_add_u64 v[188:189], v[188:189], 0, s[8:9]
	s_mov_b32 m0, s53
	ds_read_b128 v[176:179], v151 offset:49152
	ds_read_b128 v[180:183], v151 offset:50176
	ds_read_b128 v[184:187], v151 offset:51200
	ds_read_b128 v[194:197], v151 offset:52224
	ds_read_b128 v[198:201], v151 offset:53248
	ds_read_b128 v[202:205], v151 offset:54272
	ds_read_b128 v[206:209], v151 offset:55296
	ds_read_b128 v[210:213], v151 offset:56320
	global_load_lds_dwordx4 v[188:189], off
	s_add_i32 m0, s53, 0x2000
	s_add_u32 s58, s58, 0x40080
	v_lshl_add_u64 v[188:189], v[214:215], 0, s[8:9]
	s_addc_u32 s59, s59, 0
	s_add_i32 s53, s62, s24
	global_load_lds_dwordx4 v[188:189], off
	v_lshl_add_u64 v[188:189], s[58:59], 0, v[0:1]
	s_mov_b32 m0, s53
	s_nop 0
	global_load_lds_dwordx4 v[188:189], off
	v_lshl_add_u64 v[188:189], s[58:59], 0, v[134:135]
	s_add_i32 m0, s53, 0x2000
	s_nop 0
	global_load_lds_dwordx4 v[188:189], off
	v_lshl_add_u64 v[188:189], v[216:217], 0, s[8:9]
	s_mov_b32 m0, s29
	s_nop 0
	global_load_lds_dwordx4 v[188:189], off
	v_lshl_add_u64 v[188:189], v[218:219], 0, s[8:9]
	s_mov_b32 m0, s55
	s_nop 0
	global_load_lds_dwordx4 v[188:189], off
	s_waitcnt vmcnt(8)
	s_waitcnt lgkmcnt(0)
	s_barrier
	s_setprio 1
	s_waitcnt lgkmcnt(0)
	v_mfma_f32_16x16x32_bf16 v[62:65], v[140:143], v[176:179], v[62:65]
	v_mfma_f32_16x16x32_bf16 v[58:61], v[152:155], v[176:179], v[58:61]
	v_mfma_f32_16x16x32_bf16 v[46:49], v[140:143], v[184:187], v[46:49]
	v_mfma_f32_16x16x32_bf16 v[42:45], v[152:155], v[184:187], v[42:45]
	v_mfma_f32_16x16x32_bf16 v[30:33], v[140:143], v[198:201], v[30:33]
	v_mfma_f32_16x16x32_bf16 v[26:29], v[152:155], v[198:201], v[26:29]
	v_mfma_f32_16x16x32_bf16 v[14:17], v[140:143], v[206:209], v[14:17]
	v_mfma_f32_16x16x32_bf16 v[10:13], v[152:155], v[206:209], v[10:13]
	v_mfma_f32_16x16x32_bf16 v[62:65], v[144:147], v[180:183], v[62:65]
	v_mfma_f32_16x16x32_bf16 v[58:61], v[156:159], v[180:183], v[58:61]
	v_mfma_f32_16x16x32_bf16 v[46:49], v[144:147], v[194:197], v[46:49]
	v_mfma_f32_16x16x32_bf16 v[42:45], v[156:159], v[194:197], v[42:45]
	v_mfma_f32_16x16x32_bf16 v[30:33], v[144:147], v[202:205], v[30:33]
	v_mfma_f32_16x16x32_bf16 v[26:29], v[156:159], v[202:205], v[26:29]
	v_mfma_f32_16x16x32_bf16 v[14:17], v[144:147], v[210:213], v[14:17]
	v_mfma_f32_16x16x32_bf16 v[10:13], v[156:159], v[210:213], v[10:13]
	s_setprio 0
	s_setprio 1
	v_mfma_f32_16x16x32_bf16 v[54:57], v[160:163], v[176:179], v[54:57]
	v_mfma_f32_16x16x32_bf16 v[50:53], v[168:171], v[176:179], v[50:53]
	v_mfma_f32_16x16x32_bf16 v[38:41], v[160:163], v[184:187], v[38:41]
	v_mfma_f32_16x16x32_bf16 v[34:37], v[168:171], v[184:187], v[34:37]
	v_mfma_f32_16x16x32_bf16 v[22:25], v[160:163], v[198:201], v[22:25]
	v_mfma_f32_16x16x32_bf16 v[18:21], v[168:171], v[198:201], v[18:21]
	v_mfma_f32_16x16x32_bf16 v[6:9], v[160:163], v[206:209], v[6:9]
	v_mfma_f32_16x16x32_bf16 v[2:5], v[168:171], v[206:209], v[2:5]
	v_mfma_f32_16x16x32_bf16 v[54:57], v[164:167], v[180:183], v[54:57]
	v_mfma_f32_16x16x32_bf16 v[50:53], v[172:175], v[180:183], v[50:53]
	v_mfma_f32_16x16x32_bf16 v[38:41], v[164:167], v[194:197], v[38:41]
	v_mfma_f32_16x16x32_bf16 v[34:37], v[172:175], v[194:197], v[34:37]
	v_mfma_f32_16x16x32_bf16 v[22:25], v[164:167], v[202:205], v[22:25]
	v_mfma_f32_16x16x32_bf16 v[18:21], v[172:175], v[202:205], v[18:21]
	v_mfma_f32_16x16x32_bf16 v[6:9], v[164:167], v[210:213], v[6:9]
	v_mfma_f32_16x16x32_bf16 v[2:5], v[172:175], v[210:213], v[2:5]
	s_setprio 0
	s_barrier
	s_add_i32 s52, s52, 2
	s_add_u32 s18, s18, 0x100
	s_addc_u32 s19, s19, 0
	s_add_u32 s43, s43, 0x100
	s_addc_u32 s45, s45, 0
	s_cmp_gt_u32 s52, 13

; template <class Epi, class Sched, bool ALIGN_EPI = false, bool SP2 = false>
; __device__ __forceinline__ void gemm_phase(PG8_LAS unsigned char* lds, const Gemm g, const Sched& S, const Epi& E) {
;     ...
;         const bool has_next = S.next(ui + 1, nxt);
;         const char* nA = has_next ? (const char*)g.A + (size_t)nxt.pm * tstep : cA; const char* nB = has_next ? (const char*)g.Bt + (size_t)nxt.pn * tstep : cB;
;     ...
; #pragma unroll
;         for (int a = 0; a < 2; ++a)
; #pragma unroll
;             for (int b = 0; b < 2; ++b)
; #pragma unroll
;                 for (int m = 0; m < 4; ++m)
; #pragma unroll
;                     for (int n = 0; n < 2; ++n) acc[a][b][m][n] = (f32x4){0.f, 0.f, 0.f, 0.f};
.LBB0_556:
	s_ashr_i32 s43, s42, 31
	s_lshl_b64 s[30:31], s[42:43], 19
	s_add_u32 s46, s96, s30
	s_addc_u32 s47, s97, s31
	s_and_b64 s[30:31], s[44:45], exec
	s_cselect_b32 s30, s47, s19
	s_cselect_b32 s31, s46, s18
	s_ashr_i32 s41, s40, 31
	s_lshl_b64 s[34:35], s[40:41], 19
	s_add_u32 s48, s24, s34
	s_addc_u32 s49, s25, s35
	s_and_b64 s[34:35], s[44:45], exec
	s_cselect_b32 s34, s49, s57
	s_cselect_b32 s35, s48, s56
	s_add_u32 s18, s18, 0x40080
	s_addc_u32 s19, s19, 0
	s_add_u32 s41, s56, 0x100

; template <class Epi, class Sched, bool ALIGN_EPI = false, bool SP2 = false>
; __device__ __forceinline__ void gemm_phase(PG8_LAS unsigned char* lds, const Gemm g, const Sched& S, const Epi& E) {
;     ...
;         for (int t = 0; t < nt; t += 2) {
;     ...
; #pragma unroll
;         for (int a = 0; a < 2; ++a)
; #pragma unroll
;             for (int b = 0; b < 2; ++b)
; #pragma unroll
;                 for (int m = 0; m < 4; ++m)
; #pragma unroll
;                     for (int n = 0; n < 2; ++n) acc[a][b][m][n] = (f32x4){0.f, 0.f, 0.f, 0.f};
	s_addc_u32 s43, s57, 0
	s_mov_b32 s52, -2


; template <class Epi, class Sched, bool ALIGN_EPI = false, bool SP2 = false>
; __device__ __forceinline__ void gemm_phase(PG8_LAS unsigned char* lds, const Gemm g, const Sched& S, const Epi& E) {
;     ...
; #pragma unroll
;         for (int a = 0; a < 2; ++a)
; #pragma unroll
;             for (int b = 0; b < 2; ++b)
; #pragma unroll
;                 for (int m = 0; m < 4; ++m)
; #pragma unroll
;                     for (int n = 0; n < 2; ++n) acc[a][b][m][n] = (f32x4){0.f, 0.f, 0.f, 0.f};
	s_waitcnt vmcnt(0)


; #define PG8_STAGE(bufoff, gbase, voff) do { _Pragma("unroll") for (int _i = 0; _i < 2; ++_i) \
;         __builtin_amdgcn_global_load_lds((const unsigned*)((const char*)(gbase) + (voff)[_i]), (PG8_LAS unsigned*)(lds + (bufoff) + ldsw + _i * 8192), 16, 0, 0); } while (0)
; #define PG8_LDA(dst, b, h) do { _Pragma("unroll") for (int m = 0; m < 4; ++m) _Pragma("unroll") for (int k = 0; k < 2; ++k) dst[m][k] = *(const PG8_LAS bf16x8*)(lds + PG8_SA(b, h) + aoff + m * 2048 + k * 1024); } while (0)
; #define PG8_LDB(dst, b, h) do { _Pragma("unroll") for (int n = 0; n < 2; ++n) _Pragma("unroll") for (int k = 0; k < 2; ++k) dst[n][k] = *(const PG8_LAS bf16x8*)(lds + PG8_SB(b, h) + boff + n * 2048 + k * 1024); } while (0)
; #define PG8_MMA(ai, bj, At, Bt) do { __builtin_amdgcn_s_setprio(1); _Pragma("unroll") for (int m = 0; m < 4; ++m) _Pragma("unroll") for (int n = 0; n < 2; ++n) _Pragma("unroll") for (int k = 0; k < 2; ++k) \
;         acc[ai][bj][m][n] = __builtin_amdgcn_mfma_f32_16x16x32_bf16(Bt[n][k], At[m][k], acc[ai][bj][m][n], 0, 0, 0); __builtin_amdgcn_s_setprio(0); } while (0)
; #define PG8_WAIT_V(n) asm volatile("s_waitcnt vmcnt(" #n ")" ::: "memory")
; #define PG8_WAIT_L(n) asm volatile("s_waitcnt lgkmcnt(" #n ")" ::: "memory")
; #define PG8_BAR __builtin_amdgcn_s_barrier()
; #define PG8_SCHED __builtin_amdgcn_sched_barrier(0)
; template <class Epi, class Sched, bool ALIGN_EPI = false, bool SP2 = false>
; __device__ __forceinline__ void gemm_phase(PG8_LAS unsigned char* lds, const Gemm g, const Sched& S, const Epi& E) {
;     ...
;             const bool last = (t == nt - 2);
;             const char* a1 = cA + (size_t)(t + 1) * kstep;
;             const char* a2 = last ? nA : cA + (size_t)(t + 2) * kstep; const char* b2 = last ? nB : cB + (size_t)(t + 2) * kstep;
;             const char* a3 = a2 + kstep; const char* b3 = b2 + kstep;
;             if (last && has_next) S.a_ready(nxt);
;             if constexpr (SP2) {
;             PG8_LDB(B0, 0, 0); PG8_LDB(B1, 0, 1); PG8_SCHED; PG8_LDA(At, 0, 0); PG8_STAGE(PG8_SA(1, 1), a1 + hstep, voffA);
;             PG8_WAIT_V(8); PG8_WAIT_L(0); PG8_BAR; PG8_MMA(0, 0, At, B0); PG8_MMA(0, 1, At, B1); PG8_BAR; PG8_SCHED;
;             PG8_LDA(At, 0, 1); PG8_STAGE(PG8_SB(0, 0), b2, voffB); PG8_STAGE(PG8_SB(0, 1), b2 + hstep, voffB); PG8_STAGE(PG8_SA(0, 0), a2, voffA);
	s_add_u32 s53, s18, 0xfffc0080
	s_addc_u32 s56, s19, -1
	s_add_i32 s60, 0, 0x10000
	s_cmp_eq_u32 s52, 12
	s_cselect_b32 s59, s30, s56
	s_cselect_b32 s58, s31, s53
	s_cselect_b32 s57, s34, s43
	s_cselect_b32 s56, s35, s41
	s_add_i32 s53, 0, 0x14000
	v_add_u32_e32 v152, s60, v161
	v_add_u32_e32 v172, s53, v161
	ds_read_b128 v[140:143], v152
	ds_read_b128 v[144:147], v152 offset:1024
	ds_read_b128 v[148:151], v152 offset:2048
	ds_read_b128 v[152:155], v152 offset:3072
	ds_read_b128 v[156:159], v172
	ds_read_b128 v[164:167], v172 offset:1024
	ds_read_b128 v[168:171], v172 offset:2048
	ds_read_b128 v[172:175], v172 offset:3072
	v_lshl_add_u64 v[188:189], s[18:19], 0, v[136:137]
	s_add_i32 m0, s26, 0xc000
	ds_read_b128 v[176:179], v163
	ds_read_b128 v[180:183], v163 offset:1024
	ds_read_b128 v[184:187], v163 offset:2048
	ds_read_b128 v[194:197], v163 offset:3072
	ds_read_b128 v[198:201], v163 offset:4096
	ds_read_b128 v[202:205], v163 offset:5120
	ds_read_b128 v[206:209], v163 offset:6144
	ds_read_b128 v[210:213], v163 offset:7168
	global_load_lds_dwordx4 v[188:189], off
	v_lshl_add_u64 v[188:189], s[18:19], 0, v[138:139]
	s_add_i32 m0, s26, 0xe000
	s_nop 0
	global_load_lds_dwordx4 v[188:189], off
	s_waitcnt vmcnt(8)
	s_waitcnt lgkmcnt(0)
	s_barrier
	s_setprio 1
	s_waitcnt lgkmcnt(0)
	v_mfma_f32_16x16x32_bf16 v[126:129], v[140:143], v[176:179], 0
	v_mfma_f32_16x16x32_bf16 v[122:125], v[148:151], v[176:179], 0
	v_mfma_f32_16x16x32_bf16 v[118:121], v[140:143], v[184:187], 0
	v_mfma_f32_16x16x32_bf16 v[106:109], v[148:151], v[184:187], 0
	v_mfma_f32_16x16x32_bf16 v[94:97], v[140:143], v[198:201], 0
	v_mfma_f32_16x16x32_bf16 v[90:93], v[148:151], v[198:201], 0
	v_mfma_f32_16x16x32_bf16 v[78:81], v[140:143], v[206:209], 0
	v_mfma_f32_16x16x32_bf16 v[74:77], v[148:151], v[206:209], 0
	v_mfma_f32_16x16x32_bf16 v[126:129], v[144:147], v[180:183], v[126:129]
	v_mfma_f32_16x16x32_bf16 v[122:125], v[152:155], v[180:183], v[122:125]
	v_mfma_f32_16x16x32_bf16 v[118:121], v[144:147], v[194:197], v[118:121]
	v_mfma_f32_16x16x32_bf16 v[106:109], v[152:155], v[194:197], v[106:109]
	v_mfma_f32_16x16x32_bf16 v[94:97], v[144:147], v[202:205], v[94:97]
	v_mfma_f32_16x16x32_bf16 v[90:93], v[152:155], v[202:205], v[90:93]
	v_mfma_f32_16x16x32_bf16 v[78:81], v[144:147], v[210:213], v[78:81]
	v_mfma_f32_16x16x32_bf16 v[74:77], v[152:155], v[210:213], v[74:77]
	s_setprio 0
	s_setprio 1
	v_mfma_f32_16x16x32_bf16 v[114:117], v[156:159], v[176:179], 0
	v_mfma_f32_16x16x32_bf16 v[110:113], v[168:171], v[176:179], 0
	v_mfma_f32_16x16x32_bf16 v[102:105], v[156:159], v[184:187], 0
	v_mfma_f32_16x16x32_bf16 v[98:101], v[168:171], v[184:187], 0
	v_mfma_f32_16x16x32_bf16 v[86:89], v[156:159], v[198:201], 0
	v_mfma_f32_16x16x32_bf16 v[82:85], v[168:171], v[198:201], 0
	v_mfma_f32_16x16x32_bf16 v[70:73], v[156:159], v[206:209], 0
	v_mfma_f32_16x16x32_bf16 v[66:69], v[168:171], v[206:209], 0
	v_mfma_f32_16x16x32_bf16 v[114:117], v[164:167], v[180:183], v[114:117]
	v_mfma_f32_16x16x32_bf16 v[110:113], v[172:175], v[180:183], v[110:113]
	v_mfma_f32_16x16x32_bf16 v[102:105], v[164:167], v[194:197], v[102:105]
	v_mfma_f32_16x16x32_bf16 v[98:101], v[172:175], v[194:197], v[98:101]
	v_mfma_f32_16x16x32_bf16 v[86:89], v[164:167], v[202:205], v[86:89]
	v_mfma_f32_16x16x32_bf16 v[82:85], v[172:175], v[202:205], v[82:85]
	v_mfma_f32_16x16x32_bf16 v[70:73], v[164:167], v[210:213], v[70:73]
	v_mfma_f32_16x16x32_bf16 v[66:69], v[172:175], v[210:213], v[66:69]
	s_setprio 0
	s_barrier
	s_add_i32 s60, s60, s23
	v_lshl_add_u64 v[188:189], s[56:57], 0, v[0:1]
	s_mov_b32 m0, s60
	ds_read_b128 v[176:179], v163 offset:16384
	ds_read_b128 v[180:183], v163 offset:17408
	ds_read_b128 v[184:187], v163 offset:18432
	ds_read_b128 v[194:197], v163 offset:19456
	ds_read_b128 v[198:201], v163 offset:20480
	ds_read_b128 v[202:205], v163 offset:21504
	ds_read_b128 v[206:209], v163 offset:22528
	ds_read_b128 v[210:213], v163 offset:23552
	global_load_lds_dwordx4 v[188:189], off
	s_add_i32 m0, s60, 0x2000
	s_add_u32 s60, s56, 0x40000
	v_lshl_add_u64 v[214:215], s[56:57], 0, v[134:135]
	s_addc_u32 s61, s57, 0
	s_add_i32 s53, s53, s23
	global_load_lds_dwordx4 v[214:215], off
	v_lshl_add_u64 v[216:217], s[60:61], 0, v[0:1]
	s_mov_b32 m0, s53
	v_lshl_add_u64 v[218:219], s[58:59], 0, v[132:133]
	global_load_lds_dwordx4 v[216:217], off
	v_lshl_add_u64 v[216:217], s[60:61], 0, v[134:135]
	s_add_i32 m0, s53, 0x2000
	s_nop 0
	global_load_lds_dwordx4 v[216:217], off
	v_lshl_add_u64 v[216:217], s[58:59], 0, v[130:131]
	s_mov_b32 m0, s26
	s_nop 0
	global_load_lds_dwordx4 v[216:217], off
	s_mov_b32 m0, s27
	s_nop 0
	global_load_lds_dwordx4 v[218:219], off
	s_waitcnt vmcnt(8)
	s_waitcnt lgkmcnt(0)
	s_barrier
; #define PG8_STAGE(bufoff, gbase, voff) do { _Pragma("unroll") for (int _i = 0; _i < 2; ++_i) \
;         __builtin_amdgcn_global_load_lds((const unsigned*)((const char*)(gbase) + (voff)[_i]), (PG8_LAS unsigned*)(lds + (bufoff) + ldsw + _i * 8192), 16, 0, 0); } while (0)
; #define PG8_LDA(dst, b, h) do { _Pragma("unroll") for (int m = 0; m < 4; ++m) _Pragma("unroll") for (int k = 0; k < 2; ++k) dst[m][k] = *(const PG8_LAS bf16x8*)(lds + PG8_SA(b, h) + aoff + m * 2048 + k * 1024); } while (0)
; #define PG8_LDB(dst, b, h) do { _Pragma("unroll") for (int n = 0; n < 2; ++n) _Pragma("unroll") for (int k = 0; k < 2; ++k) dst[n][k] = *(const PG8_LAS bf16x8*)(lds + PG8_SB(b, h) + boff + n * 2048 + k * 1024); } while (0)
; #define PG8_MMA(ai, bj, At, Bt) do { __builtin_amdgcn_s_setprio(1); _Pragma("unroll") for (int m = 0; m < 4; ++m) _Pragma("unroll") for (int n = 0; n < 2; ++n) _Pragma("unroll") for (int k = 0; k < 2; ++k) \
;         acc[ai][bj][m][n] = __builtin_amdgcn_mfma_f32_16x16x32_bf16(Bt[n][k], At[m][k], acc[ai][bj][m][n], 0, 0, 0); __builtin_amdgcn_s_setprio(0); } while (0)
; #define PG8_WAIT_V(n) asm volatile("s_waitcnt vmcnt(" #n ")" ::: "memory")
; #define PG8_WAIT_L(n) asm volatile("s_waitcnt lgkmcnt(" #n ")" ::: "memory")
; #define PG8_BAR __builtin_amdgcn_s_barrier()
; #define PG8_SCHED __builtin_amdgcn_sched_barrier(0)
; template <class Epi, class Sched, bool ALIGN_EPI = false, bool SP2 = false>
; __device__ __forceinline__ void gemm_phase(PG8_LAS unsigned char* lds, const Gemm g, const Sched& S, const Epi& E) {
;     ...
;             PG8_WAIT_V(8); PG8_WAIT_L(0); PG8_BAR; PG8_MMA(1, 0, At, B0); PG8_MMA(1, 1, At, B1); PG8_BAR; PG8_SCHED;
;             PG8_LDB(B0, 1, 0); PG8_LDB(B1, 1, 1); PG8_SCHED; PG8_LDA(At, 1, 0); PG8_STAGE(PG8_SA(0, 1), a2 + hstep, voffA);
;             PG8_WAIT_V(8); PG8_WAIT_L(0); PG8_BAR; PG8_MMA(0, 0, At, B0); PG8_MMA(0, 1, At, B1); PG8_BAR; PG8_SCHED;
	s_setprio 1
	s_waitcnt lgkmcnt(0)
	v_mfma_f32_16x16x32_bf16 v[62:65], v[140:143], v[176:179], 0
	v_mfma_f32_16x16x32_bf16 v[58:61], v[148:151], v[176:179], 0
	v_mfma_f32_16x16x32_bf16 v[46:49], v[140:143], v[184:187], 0
	v_mfma_f32_16x16x32_bf16 v[42:45], v[148:151], v[184:187], 0
	v_mfma_f32_16x16x32_bf16 v[30:33], v[140:143], v[198:201], 0
	v_mfma_f32_16x16x32_bf16 v[26:29], v[148:151], v[198:201], 0
	v_mfma_f32_16x16x32_bf16 v[14:17], v[140:143], v[206:209], 0
	v_mfma_f32_16x16x32_bf16 v[10:13], v[148:151], v[206:209], 0
	v_mfma_f32_16x16x32_bf16 v[62:65], v[144:147], v[180:183], v[62:65]
	v_mfma_f32_16x16x32_bf16 v[58:61], v[152:155], v[180:183], v[58:61]
	v_mfma_f32_16x16x32_bf16 v[46:49], v[144:147], v[194:197], v[46:49]
	v_mfma_f32_16x16x32_bf16 v[42:45], v[152:155], v[194:197], v[42:45]
	v_mfma_f32_16x16x32_bf16 v[30:33], v[144:147], v[202:205], v[30:33]
	v_mfma_f32_16x16x32_bf16 v[26:29], v[152:155], v[202:205], v[26:29]
	v_mfma_f32_16x16x32_bf16 v[14:17], v[144:147], v[210:213], v[14:17]
	v_mfma_f32_16x16x32_bf16 v[10:13], v[152:155], v[210:213], v[10:13]
	s_setprio 0
	s_setprio 1
	v_mfma_f32_16x16x32_bf16 v[54:57], v[156:159], v[176:179], 0
	v_mfma_f32_16x16x32_bf16 v[50:53], v[168:171], v[176:179], 0
	v_mfma_f32_16x16x32_bf16 v[38:41], v[156:159], v[184:187], 0
	v_mfma_f32_16x16x32_bf16 v[34:37], v[168:171], v[184:187], 0
	v_mfma_f32_16x16x32_bf16 v[22:25], v[156:159], v[198:201], 0
	v_mfma_f32_16x16x32_bf16 v[18:21], v[168:171], v[198:201], 0
	v_mfma_f32_16x16x32_bf16 v[6:9], v[156:159], v[206:209], 0
	v_mfma_f32_16x16x32_bf16 v[2:5], v[168:171], v[206:209], 0
	v_mfma_f32_16x16x32_bf16 v[54:57], v[164:167], v[180:183], v[54:57]
	v_mfma_f32_16x16x32_bf16 v[50:53], v[172:175], v[180:183], v[50:53]
	v_mfma_f32_16x16x32_bf16 v[38:41], v[164:167], v[194:197], v[38:41]
	v_mfma_f32_16x16x32_bf16 v[34:37], v[172:175], v[194:197], v[34:37]
	v_mfma_f32_16x16x32_bf16 v[22:25], v[164:167], v[202:205], v[22:25]
	v_mfma_f32_16x16x32_bf16 v[18:21], v[172:175], v[202:205], v[18:21]
	v_mfma_f32_16x16x32_bf16 v[6:9], v[164:167], v[210:213], v[6:9]
	v_mfma_f32_16x16x32_bf16 v[2:5], v[172:175], v[210:213], v[2:5]
	s_setprio 0
	s_barrier
	s_add_i32 s53, 0, 0x18000
	s_add_i32 s60, 0, 0x1c000
	v_add_u32_e32 v152, s53, v161
	v_add_u32_e32 v172, s60, v161
	ds_read_b128 v[140:143], v152
	ds_read_b128 v[144:147], v152 offset:1024
	ds_read_b128 v[148:151], v152 offset:2048
	ds_read_b128 v[152:155], v152 offset:3072
	ds_read_b128 v[156:159], v172
	ds_read_b128 v[164:167], v172 offset:1024
	ds_read_b128 v[168:171], v172 offset:2048
	ds_read_b128 v[172:175], v172 offset:3072
	s_add_u32 s58, s58, 0x40000
	s_addc_u32 s59, s59, 0
	s_mov_b32 m0, s28
	v_lshl_add_u64 v[220:221], s[58:59], 0, v[130:131]
	ds_read_b128 v[176:179], v163 offset:32768
	ds_read_b128 v[180:183], v163 offset:33792
	ds_read_b128 v[184:187], v163 offset:34816
	ds_read_b128 v[194:197], v163 offset:35840
	ds_read_b128 v[198:201], v163 offset:36864
	ds_read_b128 v[202:205], v163 offset:37888
	ds_read_b128 v[206:209], v163 offset:38912
	ds_read_b128 v[210:213], v163 offset:39936
	global_load_lds_dwordx4 v[220:221], off
	v_lshl_add_u64 v[220:221], s[58:59], 0, v[132:133]
	s_mov_b32 m0, s29
	s_nop 0
	global_load_lds_dwordx4 v[220:221], off
	s_waitcnt vmcnt(8)
	s_waitcnt lgkmcnt(0)
	s_barrier
	s_setprio 1
	s_waitcnt lgkmcnt(0)
	v_mfma_f32_16x16x32_bf16 v[126:129], v[140:143], v[176:179], v[126:129]
	v_mfma_f32_16x16x32_bf16 v[122:125], v[148:151], v[176:179], v[122:125]
	v_mfma_f32_16x16x32_bf16 v[118:121], v[140:143], v[184:187], v[118:121]
	v_mfma_f32_16x16x32_bf16 v[106:109], v[148:151], v[184:187], v[106:109]
	v_mfma_f32_16x16x32_bf16 v[94:97], v[140:143], v[198:201], v[94:97]
	v_mfma_f32_16x16x32_bf16 v[90:93], v[148:151], v[198:201], v[90:93]
	v_mfma_f32_16x16x32_bf16 v[78:81], v[140:143], v[206:209], v[78:81]
	v_mfma_f32_16x16x32_bf16 v[74:77], v[148:151], v[206:209], v[74:77]
	v_mfma_f32_16x16x32_bf16 v[126:129], v[144:147], v[180:183], v[126:129]
	v_mfma_f32_16x16x32_bf16 v[122:125], v[152:155], v[180:183], v[122:125]
	v_mfma_f32_16x16x32_bf16 v[118:121], v[144:147], v[194:197], v[118:121]
	v_mfma_f32_16x16x32_bf16 v[106:109], v[152:155], v[194:197], v[106:109]
	v_mfma_f32_16x16x32_bf16 v[94:97], v[144:147], v[202:205], v[94:97]
	v_mfma_f32_16x16x32_bf16 v[90:93], v[152:155], v[202:205], v[90:93]
	v_mfma_f32_16x16x32_bf16 v[78:81], v[144:147], v[210:213], v[78:81]
	v_mfma_f32_16x16x32_bf16 v[74:77], v[152:155], v[210:213], v[74:77]
	s_setprio 0
	s_setprio 1
	v_mfma_f32_16x16x32_bf16 v[114:117], v[156:159], v[176:179], v[114:117]
	v_mfma_f32_16x16x32_bf16 v[110:113], v[168:171], v[176:179], v[110:113]
	v_mfma_f32_16x16x32_bf16 v[102:105], v[156:159], v[184:187], v[102:105]
	v_mfma_f32_16x16x32_bf16 v[98:101], v[168:171], v[184:187], v[98:101]
	v_mfma_f32_16x16x32_bf16 v[86:89], v[156:159], v[198:201], v[86:89]
	v_mfma_f32_16x16x32_bf16 v[82:85], v[168:171], v[198:201], v[82:85]
	v_mfma_f32_16x16x32_bf16 v[70:73], v[156:159], v[206:209], v[70:73]
	v_mfma_f32_16x16x32_bf16 v[66:69], v[168:171], v[206:209], v[66:69]
	v_mfma_f32_16x16x32_bf16 v[114:117], v[164:167], v[180:183], v[114:117]
	v_mfma_f32_16x16x32_bf16 v[110:113], v[172:175], v[180:183], v[110:113]
	v_mfma_f32_16x16x32_bf16 v[102:105], v[164:167], v[194:197], v[102:105]
	v_mfma_f32_16x16x32_bf16 v[98:101], v[172:175], v[194:197], v[98:101]
	v_mfma_f32_16x16x32_bf16 v[86:89], v[164:167], v[202:205], v[86:89]
	v_mfma_f32_16x16x32_bf16 v[82:85], v[172:175], v[202:205], v[82:85]
	v_mfma_f32_16x16x32_bf16 v[70:73], v[164:167], v[210:213], v[70:73]
	v_mfma_f32_16x16x32_bf16 v[66:69], v[172:175], v[210:213], v[66:69]
	s_setprio 0
	s_barrier
; #define PG8_STAGE(bufoff, gbase, voff) do { _Pragma("unroll") for (int _i = 0; _i < 2; ++_i) \
;         __builtin_amdgcn_global_load_lds((const unsigned*)((const char*)(gbase) + (voff)[_i]), (PG8_LAS unsigned*)(lds + (bufoff) + ldsw + _i * 8192), 16, 0, 0); } while (0)
; #define PG8_LDA(dst, b, h) do { _Pragma("unroll") for (int m = 0; m < 4; ++m) _Pragma("unroll") for (int k = 0; k < 2; ++k) dst[m][k] = *(const PG8_LAS bf16x8*)(lds + PG8_SA(b, h) + aoff + m * 2048 + k * 1024); } while (0)
; #define PG8_MMA(ai, bj, At, Bt) do { __builtin_amdgcn_s_setprio(1); _Pragma("unroll") for (int m = 0; m < 4; ++m) _Pragma("unroll") for (int n = 0; n < 2; ++n) _Pragma("unroll") for (int k = 0; k < 2; ++k) \
;         acc[ai][bj][m][n] = __builtin_amdgcn_mfma_f32_16x16x32_bf16(Bt[n][k], At[m][k], acc[ai][bj][m][n], 0, 0, 0); __builtin_amdgcn_s_setprio(0); } while (0)
; #define PG8_WAIT_V(n) asm volatile("s_waitcnt vmcnt(" #n ")" ::: "memory")
; #define PG8_WAIT_L(n) asm volatile("s_waitcnt lgkmcnt(" #n ")" ::: "memory")
; #define PG8_BAR __builtin_amdgcn_s_barrier()
; #define PG8_SCHED __builtin_amdgcn_sched_barrier(0)
; template <class Epi, class Sched, bool ALIGN_EPI = false, bool SP2 = false>
; __device__ __forceinline__ void gemm_phase(PG8_LAS unsigned char* lds, const Gemm g, const Sched& S, const Epi& E) {
;     ...
;         for (int t = 0; t < nt; t += 2) {
;     ...
;             PG8_LDA(At, 1, 1); PG8_STAGE(PG8_SB(1, 0), b3, voffB); PG8_STAGE(PG8_SB(1, 1), b3 + hstep, voffB); PG8_STAGE(PG8_SA(1, 0), a3, voffA);
;             PG8_WAIT_V(8); PG8_WAIT_L(0); PG8_BAR; PG8_MMA(1, 0, At, B0); PG8_MMA(1, 1, At, B1); PG8_BAR; PG8_SCHED;
	s_add_i32 s53, s53, s23
	v_lshl_add_u64 v[188:189], v[188:189], 0, s[8:9]
	s_mov_b32 m0, s53
	ds_read_b128 v[176:179], v163 offset:49152
	ds_read_b128 v[180:183], v163 offset:50176
	ds_read_b128 v[184:187], v163 offset:51200
	ds_read_b128 v[194:197], v163 offset:52224
	ds_read_b128 v[198:201], v163 offset:53248
	ds_read_b128 v[202:205], v163 offset:54272
	ds_read_b128 v[206:209], v163 offset:55296
	ds_read_b128 v[210:213], v163 offset:56320
	global_load_lds_dwordx4 v[188:189], off
	s_add_i32 m0, s53, 0x2000
	s_add_u32 s56, s56, 0x40080
	v_lshl_add_u64 v[188:189], v[214:215], 0, s[8:9]
	s_addc_u32 s57, s57, 0
	s_add_i32 s53, s60, s23
	global_load_lds_dwordx4 v[188:189], off
	v_lshl_add_u64 v[188:189], s[56:57], 0, v[0:1]
	s_mov_b32 m0, s53
	s_nop 0
	global_load_lds_dwordx4 v[188:189], off
	v_lshl_add_u64 v[188:189], s[56:57], 0, v[134:135]
	s_add_i32 m0, s53, 0x2000
	s_nop 0
	global_load_lds_dwordx4 v[188:189], off
	v_lshl_add_u64 v[188:189], v[216:217], 0, s[8:9]
	s_mov_b32 m0, s22
	s_nop 0
	global_load_lds_dwordx4 v[188:189], off
	v_lshl_add_u64 v[188:189], v[218:219], 0, s[8:9]
	s_mov_b32 m0, s51
	s_nop 0
	global_load_lds_dwordx4 v[188:189], off
	s_waitcnt vmcnt(8)
	s_waitcnt lgkmcnt(0)
	s_barrier
	s_setprio 1
	s_waitcnt lgkmcnt(0)
	v_mfma_f32_16x16x32_bf16 v[62:65], v[140:143], v[176:179], v[62:65]
	v_mfma_f32_16x16x32_bf16 v[58:61], v[148:151], v[176:179], v[58:61]
	v_mfma_f32_16x16x32_bf16 v[46:49], v[140:143], v[184:187], v[46:49]
	v_mfma_f32_16x16x32_bf16 v[42:45], v[148:151], v[184:187], v[42:45]
	v_mfma_f32_16x16x32_bf16 v[30:33], v[140:143], v[198:201], v[30:33]
	v_mfma_f32_16x16x32_bf16 v[26:29], v[148:151], v[198:201], v[26:29]
	v_mfma_f32_16x16x32_bf16 v[14:17], v[140:143], v[206:209], v[14:17]
	v_mfma_f32_16x16x32_bf16 v[10:13], v[148:151], v[206:209], v[10:13]
	v_mfma_f32_16x16x32_bf16 v[62:65], v[144:147], v[180:183], v[62:65]
	v_mfma_f32_16x16x32_bf16 v[58:61], v[152:155], v[180:183], v[58:61]
	v_mfma_f32_16x16x32_bf16 v[46:49], v[144:147], v[194:197], v[46:49]
	v_mfma_f32_16x16x32_bf16 v[42:45], v[152:155], v[194:197], v[42:45]
	v_mfma_f32_16x16x32_bf16 v[30:33], v[144:147], v[202:205], v[30:33]
	v_mfma_f32_16x16x32_bf16 v[26:29], v[152:155], v[202:205], v[26:29]
	v_mfma_f32_16x16x32_bf16 v[14:17], v[144:147], v[210:213], v[14:17]
	v_mfma_f32_16x16x32_bf16 v[10:13], v[152:155], v[210:213], v[10:13]
	s_setprio 0
	s_setprio 1
	v_mfma_f32_16x16x32_bf16 v[54:57], v[156:159], v[176:179], v[54:57]
	v_mfma_f32_16x16x32_bf16 v[50:53], v[168:171], v[176:179], v[50:53]
	v_mfma_f32_16x16x32_bf16 v[38:41], v[156:159], v[184:187], v[38:41]
	v_mfma_f32_16x16x32_bf16 v[34:37], v[168:171], v[184:187], v[34:37]
	v_mfma_f32_16x16x32_bf16 v[22:25], v[156:159], v[198:201], v[22:25]
	v_mfma_f32_16x16x32_bf16 v[18:21], v[168:171], v[198:201], v[18:21]
	v_mfma_f32_16x16x32_bf16 v[6:9], v[156:159], v[206:209], v[6:9]
	v_mfma_f32_16x16x32_bf16 v[2:5], v[168:171], v[206:209], v[2:5]
	v_mfma_f32_16x16x32_bf16 v[54:57], v[164:167], v[180:183], v[54:57]
	v_mfma_f32_16x16x32_bf16 v[50:53], v[172:175], v[180:183], v[50:53]
	v_mfma_f32_16x16x32_bf16 v[38:41], v[164:167], v[194:197], v[38:41]
	v_mfma_f32_16x16x32_bf16 v[34:37], v[172:175], v[194:197], v[34:37]
	v_mfma_f32_16x16x32_bf16 v[22:25], v[164:167], v[202:205], v[22:25]
	v_mfma_f32_16x16x32_bf16 v[18:21], v[172:175], v[202:205], v[18:21]
	v_mfma_f32_16x16x32_bf16 v[6:9], v[164:167], v[210:213], v[6:9]
	v_mfma_f32_16x16x32_bf16 v[2:5], v[172:175], v[210:213], v[2:5]
	s_setprio 0
	s_barrier
	s_add_i32 s52, s52, 2
	s_add_u32 s18, s18, 0x100
	s_addc_u32 s19, s19, 0
	s_add_u32 s41, s41, 0x100
	s_addc_u32 s43, s43, 0
	s_cmp_gt_u32 s52, 13
